# persistent GEMM tiles: redundant barrier inside the bf16 epilogue removed (tile-start barrier already orders LDS reuse)
# speedup vs baseline: 1.0111x; 1.0009x over previous
; DEV u16 f2bf(float f) { return (u16)(pack2(f, f) & 0xffffu); }
; DEV float silu_f(float x) { return x / (1.f + __expf(-x)); }
; template <class F>
; DEV void acc_foreach(Acc& acc, int m0, int n0, F f) {
;   asm volatile("s_nop 7\n\ts_nop 7\n\ts_nop 3" ::: "memory");
;   const int tid = tidx_full();
;   const int wave = tid >> 6, lane = tid & 63;
;   const int wm = (wave >> 2) * 128, wn = (wave & 3) * 64;
;   const int lr = lane & 31, lh = lane >> 5;
; #pragma unroll
;   for (int i = 0; i < 4; ++i)
; #pragma unroll
;     for (int j = 0; j < 2; ++j)
; #pragma unroll
;       for (int r = 0; r < 16; ++r) {
;         const int m = m0 + wm + 32 * i + (r & 3) + 8 * (r >> 2) + 4 * lh;
;         const int n = n0 + wn + 32 * j + lr;
;         float v = acc[i][j][r];
;         f(m, n, v);
;         acc[i][j][r] = v;
;       }
; }
; DEV void phase_p1(const Params& p, int g, char* smem) {
;     ...
;       if (n0 < 2560) {
;         const bool dosilu = (n0 < 512) || (n0 >= 2048);
;         acc_foreach(acc, m0, n0, [&](int m, int n, float& v) {
;           const float o = dosilu ? silu_f(v) : v;
;           PHG[(size_t)m * 2560 + n] = f2bf(o);
;         });
.Lp1a_d4:
.Lp1a_nomore:
	s_cmp_gt_i32 s8, 9
	s_cbranch_scc1 .Lp1a_gt
	s_cmp_lt_u32 s8, 2
	s_cbranch_scc1 .Lp1a_silu
	s_cmp_gt_u32 s8, 7
	s_cbranch_scc1 .Lp1a_silu
	s_nop 7
	s_nop 7
	s_nop 3
	v_and_b32_e32 v160, 63, v202
	v_lshrrev_b32_e32 v161, 6, v202
	v_and_b32_e32 v164, 3, v161
	v_lshlrev_b32_e32 v164, 13, v164
	v_add_u32_e32 v164, 0x8000, v164
	v_lshrrev_b32_e32 v160, 2, v161
	v_lshl_add_u32 v164, v160, 16, v164
	v_and_b32_e32 v160, 63, v202
	v_and_b32_e32 v166, 15, v160
	v_lshrrev_b32_e32 v167, 4, v160
	v_lshl_add_u32 v168, v166, 7, v164
	v_and_b32_e32 v169, 1, v167
	v_lshl_add_u32 v168, v169, 3, v168
	v_lshrrev_b32_e32 v167, 1, v167
	v_and_b32_e32 v166, 7, v166
	v_xor_b32_e32 v166, v166, v167
	v_lshlrev_b32_e32 v166, 4, v166
	v_add_u32_e32 v170, v168, v166
	v_xor_b32_e32 v167, 0x20, v166
	v_add_u32_e32 v171, v168, v167
	v_xor_b32_e32 v167, 0x40, v166
	v_add_u32_e32 v172, v168, v167
	v_xor_b32_e32 v167, 0x60, v166
	v_add_u32_e32 v173, v168, v167
	v_and_b32_e32 v166, 31, v160
	v_lshrrev_b32_e32 v167, 5, v160
	v_lshlrev_b32_e32 v168, 7, v166
	v_lshl_add_u32 v168, v167, 3, v168
	v_add_u32_e32 v168, v164, v168
	v_and_b32_e32 v166, 7, v166
	v_lshlrev_b32_e32 v166, 4, v166
	v_lshrrev_b32_e32 v166, 3, v160
	v_and_b32_e32 v167, 7, v160
	v_lshrrev_b32_e32 v169, 2, v161
	v_lshl_add_u32 v169, v169, 7, v166
	v_add_u32_e32 v169, s5, v169
	v_mul_u32_u24_e32 v169, 0x1400, v169
	v_and_b32_e32 v168, 3, v161
	v_lshlrev_b32_e32 v168, 3, v168
	v_add_u32_e32 v168, v168, v167
	v_lshl_add_u32 v169, v168, 4, v169
	s_lshl_b32 s100, s4, 1
	v_add_u32_e32 v169, s100, v169
	v_xor_b32_e32 v167, v166, v167
	v_lshlrev_b32_e32 v167, 4, v167
	v_lshl_add_u32 v168, v166, 7, v167
	v_add_u32_e32 v168, v164, v168
	v_cvt_pk_bf16_f32 v0, v0, v1
	v_cvt_pk_bf16_f32 v1, v2, v3
	ds_write_b64 v170, v[0:1]
	v_cvt_pk_bf16_f32 v4, v4, v5
	v_cvt_pk_bf16_f32 v5, v6, v7
	ds_write_b64 v171, v[4:5]
	v_cvt_pk_bf16_f32 v8, v8, v9
	v_cvt_pk_bf16_f32 v9, v10, v11
	ds_write_b64 v172, v[8:9]
	v_cvt_pk_bf16_f32 v12, v12, v13
	v_cvt_pk_bf16_f32 v13, v14, v15
	ds_write_b64 v173, v[12:13]
	v_cvt_pk_bf16_f32 v16, v16, v17
	v_cvt_pk_bf16_f32 v17, v18, v19
	ds_write_b64 v170, v[16:17] offset:2048
	v_cvt_pk_bf16_f32 v20, v20, v21
	v_cvt_pk_bf16_f32 v21, v22, v23
	ds_write_b64 v171, v[20:21] offset:2048
	v_cvt_pk_bf16_f32 v24, v24, v25
	v_cvt_pk_bf16_f32 v25, v26, v27
	ds_write_b64 v172, v[24:25] offset:2048
	v_cvt_pk_bf16_f32 v28, v28, v29
	v_cvt_pk_bf16_f32 v29, v30, v31
	ds_write_b64 v173, v[28:29] offset:2048
	v_cvt_pk_bf16_f32 v32, v32, v33
	v_cvt_pk_bf16_f32 v33, v34, v35
	ds_write_b64 v170, v[32:33] offset:4096
	v_cvt_pk_bf16_f32 v36, v36, v37
	v_cvt_pk_bf16_f32 v37, v38, v39
	ds_write_b64 v171, v[36:37] offset:4096
	v_cvt_pk_bf16_f32 v40, v40, v41
	v_cvt_pk_bf16_f32 v41, v42, v43
	ds_write_b64 v172, v[40:41] offset:4096
	v_cvt_pk_bf16_f32 v44, v44, v45
	v_cvt_pk_bf16_f32 v45, v46, v47
	ds_write_b64 v173, v[44:45] offset:4096
	v_cvt_pk_bf16_f32 v48, v48, v49
	v_cvt_pk_bf16_f32 v49, v50, v51
	ds_write_b64 v170, v[48:49] offset:6144
	v_cvt_pk_bf16_f32 v52, v52, v53
	v_cvt_pk_bf16_f32 v53, v54, v55
	ds_write_b64 v171, v[52:53] offset:6144
	v_cvt_pk_bf16_f32 v56, v56, v57
	v_cvt_pk_bf16_f32 v57, v58, v59
	ds_write_b64 v172, v[56:57] offset:6144
	v_cvt_pk_bf16_f32 v60, v60, v61
	v_cvt_pk_bf16_f32 v61, v62, v63
	ds_write_b64 v173, v[60:61] offset:6144
	s_waitcnt lgkmcnt(0)
	ds_read_b128 v[32:35], v168
	ds_read_b128 v[36:39], v168 offset:1024
	ds_read_b128 v[40:43], v168 offset:2048
	ds_read_b128 v[44:47], v168 offset:3072
	ds_read_b128 v[48:51], v168 offset:4096
	ds_read_b128 v[52:55], v168 offset:5120
	ds_read_b128 v[56:59], v168 offset:6144
	ds_read_b128 v[60:63], v168 offset:7168
	s_waitcnt lgkmcnt(7)
	global_store_dwordx4 v169, v[32:35], s[56:57]
	v_add_u32_e32 v169, 0xa000, v169
	s_waitcnt lgkmcnt(6)
	global_store_dwordx4 v169, v[36:39], s[56:57]
	v_add_u32_e32 v169, 0xa000, v169
	s_waitcnt lgkmcnt(5)
	global_store_dwordx4 v169, v[40:43], s[56:57]
	v_add_u32_e32 v169, 0xa000, v169
	s_waitcnt lgkmcnt(4)
	global_store_dwordx4 v169, v[44:47], s[56:57]
	v_add_u32_e32 v169, 0xa000, v169
	s_waitcnt lgkmcnt(3)
	global_store_dwordx4 v169, v[48:51], s[56:57]
	v_add_u32_e32 v169, 0xa000, v169
	s_waitcnt lgkmcnt(2)
	global_store_dwordx4 v169, v[52:55], s[56:57]
	v_add_u32_e32 v169, 0xa000, v169
	s_waitcnt lgkmcnt(1)
	global_store_dwordx4 v169, v[56:59], s[56:57]
	v_add_u32_e32 v169, 0xa000, v169
	s_waitcnt lgkmcnt(0)
	global_store_dwordx4 v169, v[60:63], s[56:57]
	v_add_u32_e32 v169, 0xa000, v169
	v_cvt_pk_bf16_f32 v64, v64, v65
	v_cvt_pk_bf16_f32 v65, v66, v67
	ds_write_b64 v170, v[64:65]
	v_cvt_pk_bf16_f32 v68, v68, v69
	v_cvt_pk_bf16_f32 v69, v70, v71
	ds_write_b64 v171, v[68:69]
	v_cvt_pk_bf16_f32 v72, v72, v73
	v_cvt_pk_bf16_f32 v73, v74, v75
	ds_write_b64 v172, v[72:73]
	v_cvt_pk_bf16_f32 v76, v76, v77
	v_cvt_pk_bf16_f32 v77, v78, v79
	ds_write_b64 v173, v[76:77]
	v_cvt_pk_bf16_f32 v80, v80, v81
	v_cvt_pk_bf16_f32 v81, v82, v83
	ds_write_b64 v170, v[80:81] offset:2048
	v_cvt_pk_bf16_f32 v84, v84, v85
	v_cvt_pk_bf16_f32 v85, v86, v87
	ds_write_b64 v171, v[84:85] offset:2048
	v_cvt_pk_bf16_f32 v88, v88, v89
	v_cvt_pk_bf16_f32 v89, v90, v91
	ds_write_b64 v172, v[88:89] offset:2048
	v_cvt_pk_bf16_f32 v92, v92, v93
	v_cvt_pk_bf16_f32 v93, v94, v95
	ds_write_b64 v173, v[92:93] offset:2048
	v_cvt_pk_bf16_f32 v96, v96, v97
	v_cvt_pk_bf16_f32 v97, v98, v99
	ds_write_b64 v170, v[96:97] offset:4096
	v_cvt_pk_bf16_f32 v100, v100, v101
	v_cvt_pk_bf16_f32 v101, v102, v103
	ds_write_b64 v171, v[100:101] offset:4096
	v_cvt_pk_bf16_f32 v104, v104, v105
	v_cvt_pk_bf16_f32 v105, v106, v107
	ds_write_b64 v172, v[104:105] offset:4096
	v_cvt_pk_bf16_f32 v108, v108, v109
	v_cvt_pk_bf16_f32 v109, v110, v111
	ds_write_b64 v173, v[108:109] offset:4096
	v_cvt_pk_bf16_f32 v112, v112, v113
	v_cvt_pk_bf16_f32 v113, v114, v115
	ds_write_b64 v170, v[112:113] offset:6144
	v_cvt_pk_bf16_f32 v116, v116, v117
	v_cvt_pk_bf16_f32 v117, v118, v119
	ds_write_b64 v171, v[116:117] offset:6144
	v_cvt_pk_bf16_f32 v120, v120, v121
	v_cvt_pk_bf16_f32 v121, v122, v123
	ds_write_b64 v172, v[120:121] offset:6144
	v_cvt_pk_bf16_f32 v124, v124, v125
	v_cvt_pk_bf16_f32 v125, v126, v127
	ds_write_b64 v173, v[124:125] offset:6144
	s_waitcnt lgkmcnt(0)
; DEV u16 f2bf(float f) { return (u16)(pack2(f, f) & 0xffffu); }
; DEV float silu_f(float x) { return x / (1.f + __expf(-x)); }
; DEV float sigmoid_f(float x) { return __builtin_amdgcn_rcpf(1.f + __expf(-x)); }
; DEV void phase_p1(const Params& p, int g, char* smem) {
;     ...
;       if (n0 < 2560) {
;         const bool dosilu = (n0 < 512) || (n0 >= 2048);
;         acc_foreach(acc, m0, n0, [&](int m, int n, float& v) {
;           const float o = dosilu ? silu_f(v) : v;
;           PHG[(size_t)m * 2560 + n] = f2bf(o);
;         });
;       } else {
;         acc_foreach(acc, m0, n0, [&](int m, int n, float& v) { GT[(size_t)m * 2048 + (n - 2560)] = f2bf(sigmoid_f(v)); });
	ds_read_b128 v[64:67], v168
	ds_read_b128 v[68:71], v168 offset:1024
	ds_read_b128 v[72:75], v168 offset:2048
	ds_read_b128 v[76:79], v168 offset:3072
	ds_read_b128 v[80:83], v168 offset:4096
	ds_read_b128 v[84:87], v168 offset:5120
	ds_read_b128 v[88:91], v168 offset:6144
	ds_read_b128 v[92:95], v168 offset:7168
	s_waitcnt lgkmcnt(7)
	global_store_dwordx4 v169, v[64:67], s[56:57]
	v_add_u32_e32 v169, 0xa000, v169
	s_waitcnt lgkmcnt(6)
	global_store_dwordx4 v169, v[68:71], s[56:57]
	v_add_u32_e32 v169, 0xa000, v169
	s_waitcnt lgkmcnt(5)
	global_store_dwordx4 v169, v[72:75], s[56:57]
	v_add_u32_e32 v169, 0xa000, v169
	s_waitcnt lgkmcnt(4)
	global_store_dwordx4 v169, v[76:79], s[56:57]
	v_add_u32_e32 v169, 0xa000, v169
	s_waitcnt lgkmcnt(3)
	global_store_dwordx4 v169, v[80:83], s[56:57]
	v_add_u32_e32 v169, 0xa000, v169
	s_waitcnt lgkmcnt(2)
	global_store_dwordx4 v169, v[84:87], s[56:57]
	v_add_u32_e32 v169, 0xa000, v169
	s_waitcnt lgkmcnt(1)
	global_store_dwordx4 v169, v[88:91], s[56:57]
	v_add_u32_e32 v169, 0xa000, v169
	s_waitcnt lgkmcnt(0)
	global_store_dwordx4 v169, v[92:95], s[56:57]
	v_add_u32_e32 v169, 0xa000, v169
	s_branch .LBB0_261
.Lp1a_silu:
	s_nop 7
	s_nop 7
	s_nop 3
	v_and_b32_e32 v160, 63, v202
	v_lshrrev_b32_e32 v161, 6, v202
	v_and_b32_e32 v164, 3, v161
	v_lshlrev_b32_e32 v164, 13, v164
	v_add_u32_e32 v164, 0x8000, v164
	v_lshrrev_b32_e32 v160, 2, v161
	v_lshl_add_u32 v164, v160, 16, v164
	v_and_b32_e32 v160, 63, v202
	v_and_b32_e32 v166, 15, v160
	v_lshrrev_b32_e32 v167, 4, v160
	v_lshl_add_u32 v168, v166, 7, v164
	v_and_b32_e32 v169, 1, v167
	v_lshl_add_u32 v168, v169, 3, v168
	v_lshrrev_b32_e32 v167, 1, v167
	v_and_b32_e32 v166, 7, v166
	v_xor_b32_e32 v166, v166, v167
	v_lshlrev_b32_e32 v166, 4, v166
	v_add_u32_e32 v170, v168, v166
	v_xor_b32_e32 v167, 0x20, v166
	v_add_u32_e32 v171, v168, v167
	v_xor_b32_e32 v167, 0x40, v166
	v_add_u32_e32 v172, v168, v167
	v_xor_b32_e32 v167, 0x60, v166
	v_add_u32_e32 v173, v168, v167
	v_and_b32_e32 v166, 31, v160
	v_lshrrev_b32_e32 v167, 5, v160
	v_lshlrev_b32_e32 v168, 7, v166
	v_lshl_add_u32 v168, v167, 3, v168
	v_add_u32_e32 v168, v164, v168
	v_and_b32_e32 v166, 7, v166
	v_lshlrev_b32_e32 v166, 4, v166
	v_lshrrev_b32_e32 v166, 3, v160
	v_and_b32_e32 v167, 7, v160
	v_lshrrev_b32_e32 v169, 2, v161
	v_lshl_add_u32 v169, v169, 7, v166
	v_add_u32_e32 v169, s5, v169
	v_mul_u32_u24_e32 v169, 0x1400, v169
	v_and_b32_e32 v168, 3, v161
	v_lshlrev_b32_e32 v168, 3, v168
	v_add_u32_e32 v168, v168, v167
	v_lshl_add_u32 v169, v168, 4, v169
	s_lshl_b32 s100, s4, 1
	v_add_u32_e32 v169, s100, v169
	v_xor_b32_e32 v167, v166, v167
	v_lshlrev_b32_e32 v167, 4, v167
	v_lshl_add_u32 v168, v166, 7, v167
	v_add_u32_e32 v168, v164, v168
	v_mul_f32_e32 v178, 0xbfb8aa3b, v0
	v_mul_f32_e32 v179, 0xbfb8aa3b, v1
	v_mul_f32_e32 v180, 0xbfb8aa3b, v2
	v_mul_f32_e32 v181, 0xbfb8aa3b, v3
	v_exp_f32_e32 v178, v178
	v_exp_f32_e32 v179, v179
	v_exp_f32_e32 v180, v180
	v_exp_f32_e32 v181, v181
	v_add_f32_e32 v178, 1.0, v178
	v_add_f32_e32 v179, 1.0, v179
	v_add_f32_e32 v180, 1.0, v180
	v_add_f32_e32 v181, 1.0, v181
	v_rcp_f32_e32 v178, v178
	v_rcp_f32_e32 v179, v179
	v_rcp_f32_e32 v180, v180
	v_rcp_f32_e32 v181, v181
	v_mul_f32_e32 v0, v0, v178
	v_mul_f32_e32 v1, v1, v179
	v_mul_f32_e32 v2, v2, v180
	v_mul_f32_e32 v3, v3, v181
	v_cvt_pk_bf16_f32 v0, v0, v1
	v_cvt_pk_bf16_f32 v1, v2, v3
	ds_write_b64 v170, v[0:1]
	v_mul_f32_e32 v178, 0xbfb8aa3b, v4
	v_mul_f32_e32 v179, 0xbfb8aa3b, v5
	v_mul_f32_e32 v180, 0xbfb8aa3b, v6
	v_mul_f32_e32 v181, 0xbfb8aa3b, v7
	v_exp_f32_e32 v178, v178
	v_exp_f32_e32 v179, v179
	v_exp_f32_e32 v180, v180
	v_exp_f32_e32 v181, v181
	v_add_f32_e32 v178, 1.0, v178
	v_add_f32_e32 v179, 1.0, v179
	v_add_f32_e32 v180, 1.0, v180
	v_add_f32_e32 v181, 1.0, v181
	v_rcp_f32_e32 v178, v178
	v_rcp_f32_e32 v179, v179
	v_rcp_f32_e32 v180, v180
	v_rcp_f32_e32 v181, v181
	v_mul_f32_e32 v4, v4, v178
	v_mul_f32_e32 v5, v5, v179
	v_mul_f32_e32 v6, v6, v180
	v_mul_f32_e32 v7, v7, v181
	v_cvt_pk_bf16_f32 v4, v4, v5
	v_cvt_pk_bf16_f32 v5, v6, v7
	ds_write_b64 v171, v[4:5]
	v_mul_f32_e32 v178, 0xbfb8aa3b, v8
	v_mul_f32_e32 v179, 0xbfb8aa3b, v9
	v_mul_f32_e32 v180, 0xbfb8aa3b, v10
	v_mul_f32_e32 v181, 0xbfb8aa3b, v11
	v_exp_f32_e32 v178, v178
	v_exp_f32_e32 v179, v179
	v_exp_f32_e32 v180, v180
	v_exp_f32_e32 v181, v181
	v_add_f32_e32 v178, 1.0, v178
	v_add_f32_e32 v179, 1.0, v179
	v_add_f32_e32 v180, 1.0, v180
	v_add_f32_e32 v181, 1.0, v181
	v_rcp_f32_e32 v178, v178
	v_rcp_f32_e32 v179, v179
	v_rcp_f32_e32 v180, v180
	v_rcp_f32_e32 v181, v181
	v_mul_f32_e32 v8, v8, v178
	v_mul_f32_e32 v9, v9, v179
	v_mul_f32_e32 v10, v10, v180
	v_mul_f32_e32 v11, v11, v181
	v_cvt_pk_bf16_f32 v8, v8, v9
	v_cvt_pk_bf16_f32 v9, v10, v11
	ds_write_b64 v172, v[8:9]
	v_mul_f32_e32 v178, 0xbfb8aa3b, v12
	v_mul_f32_e32 v179, 0xbfb8aa3b, v13
	v_mul_f32_e32 v180, 0xbfb8aa3b, v14
	v_mul_f32_e32 v181, 0xbfb8aa3b, v15
	v_exp_f32_e32 v178, v178
	v_exp_f32_e32 v179, v179
	v_exp_f32_e32 v180, v180
	v_exp_f32_e32 v181, v181
	v_add_f32_e32 v178, 1.0, v178
	v_add_f32_e32 v179, 1.0, v179
	v_add_f32_e32 v180, 1.0, v180
	v_add_f32_e32 v181, 1.0, v181
	v_rcp_f32_e32 v178, v178
	v_rcp_f32_e32 v179, v179
	v_rcp_f32_e32 v180, v180
	v_rcp_f32_e32 v181, v181
	v_mul_f32_e32 v12, v12, v178
	v_mul_f32_e32 v13, v13, v179
	v_mul_f32_e32 v14, v14, v180
	v_mul_f32_e32 v15, v15, v181
	v_cvt_pk_bf16_f32 v12, v12, v13
	v_cvt_pk_bf16_f32 v13, v14, v15
	ds_write_b64 v173, v[12:13]
	v_mul_f32_e32 v178, 0xbfb8aa3b, v16
	v_mul_f32_e32 v179, 0xbfb8aa3b, v17
	v_mul_f32_e32 v180, 0xbfb8aa3b, v18
	v_mul_f32_e32 v181, 0xbfb8aa3b, v19
	v_exp_f32_e32 v178, v178
	v_exp_f32_e32 v179, v179
; DEV u16 f2bf(float f) { return (u16)(pack2(f, f) & 0xffffu); }
; DEV float silu_f(float x) { return x / (1.f + __expf(-x)); }
; DEV void phase_p1(const Params& p, int g, char* smem) {
;     ...
;         const bool dosilu = (n0 < 512) || (n0 >= 2048);
;         acc_foreach(acc, m0, n0, [&](int m, int n, float& v) {
;           const float o = dosilu ? silu_f(v) : v;
;           PHG[(size_t)m * 2560 + n] = f2bf(o);
;         });
	v_exp_f32_e32 v180, v180
	v_exp_f32_e32 v181, v181
	v_add_f32_e32 v178, 1.0, v178
	v_add_f32_e32 v179, 1.0, v179
	v_add_f32_e32 v180, 1.0, v180
	v_add_f32_e32 v181, 1.0, v181
	v_rcp_f32_e32 v178, v178
	v_rcp_f32_e32 v179, v179
	v_rcp_f32_e32 v180, v180
	v_rcp_f32_e32 v181, v181
	v_mul_f32_e32 v16, v16, v178
	v_mul_f32_e32 v17, v17, v179
	v_mul_f32_e32 v18, v18, v180
	v_mul_f32_e32 v19, v19, v181
	v_cvt_pk_bf16_f32 v16, v16, v17
	v_cvt_pk_bf16_f32 v17, v18, v19
	ds_write_b64 v170, v[16:17] offset:2048
	v_mul_f32_e32 v178, 0xbfb8aa3b, v20
	v_mul_f32_e32 v179, 0xbfb8aa3b, v21
	v_mul_f32_e32 v180, 0xbfb8aa3b, v22
	v_mul_f32_e32 v181, 0xbfb8aa3b, v23
	v_exp_f32_e32 v178, v178
	v_exp_f32_e32 v179, v179
	v_exp_f32_e32 v180, v180
	v_exp_f32_e32 v181, v181
	v_add_f32_e32 v178, 1.0, v178
	v_add_f32_e32 v179, 1.0, v179
	v_add_f32_e32 v180, 1.0, v180
	v_add_f32_e32 v181, 1.0, v181
	v_rcp_f32_e32 v178, v178
	v_rcp_f32_e32 v179, v179
	v_rcp_f32_e32 v180, v180
	v_rcp_f32_e32 v181, v181
	v_mul_f32_e32 v20, v20, v178
	v_mul_f32_e32 v21, v21, v179
	v_mul_f32_e32 v22, v22, v180
	v_mul_f32_e32 v23, v23, v181
	v_cvt_pk_bf16_f32 v20, v20, v21
	v_cvt_pk_bf16_f32 v21, v22, v23
	ds_write_b64 v171, v[20:21] offset:2048
	v_mul_f32_e32 v178, 0xbfb8aa3b, v24
	v_mul_f32_e32 v179, 0xbfb8aa3b, v25
	v_mul_f32_e32 v180, 0xbfb8aa3b, v26
	v_mul_f32_e32 v181, 0xbfb8aa3b, v27
	v_exp_f32_e32 v178, v178
	v_exp_f32_e32 v179, v179
	v_exp_f32_e32 v180, v180
	v_exp_f32_e32 v181, v181
	v_add_f32_e32 v178, 1.0, v178
	v_add_f32_e32 v179, 1.0, v179
	v_add_f32_e32 v180, 1.0, v180
	v_add_f32_e32 v181, 1.0, v181
	v_rcp_f32_e32 v178, v178
	v_rcp_f32_e32 v179, v179
	v_rcp_f32_e32 v180, v180
	v_rcp_f32_e32 v181, v181
	v_mul_f32_e32 v24, v24, v178
	v_mul_f32_e32 v25, v25, v179
	v_mul_f32_e32 v26, v26, v180
	v_mul_f32_e32 v27, v27, v181
	v_cvt_pk_bf16_f32 v24, v24, v25
	v_cvt_pk_bf16_f32 v25, v26, v27
	ds_write_b64 v172, v[24:25] offset:2048
	v_mul_f32_e32 v178, 0xbfb8aa3b, v28
	v_mul_f32_e32 v179, 0xbfb8aa3b, v29
	v_mul_f32_e32 v180, 0xbfb8aa3b, v30
	v_mul_f32_e32 v181, 0xbfb8aa3b, v31
	v_exp_f32_e32 v178, v178
	v_exp_f32_e32 v179, v179
	v_exp_f32_e32 v180, v180
	v_exp_f32_e32 v181, v181
	v_add_f32_e32 v178, 1.0, v178
	v_add_f32_e32 v179, 1.0, v179
	v_add_f32_e32 v180, 1.0, v180
	v_add_f32_e32 v181, 1.0, v181
	v_rcp_f32_e32 v178, v178
	v_rcp_f32_e32 v179, v179
	v_rcp_f32_e32 v180, v180
	v_rcp_f32_e32 v181, v181
	v_mul_f32_e32 v28, v28, v178
	v_mul_f32_e32 v29, v29, v179
	v_mul_f32_e32 v30, v30, v180
	v_mul_f32_e32 v31, v31, v181
	v_cvt_pk_bf16_f32 v28, v28, v29
	v_cvt_pk_bf16_f32 v29, v30, v31
	ds_write_b64 v173, v[28:29] offset:2048
	v_mul_f32_e32 v178, 0xbfb8aa3b, v32
	v_mul_f32_e32 v179, 0xbfb8aa3b, v33
	v_mul_f32_e32 v180, 0xbfb8aa3b, v34
	v_mul_f32_e32 v181, 0xbfb8aa3b, v35
	v_exp_f32_e32 v178, v178
	v_exp_f32_e32 v179, v179
	v_exp_f32_e32 v180, v180
	v_exp_f32_e32 v181, v181
	v_add_f32_e32 v178, 1.0, v178
	v_add_f32_e32 v179, 1.0, v179
	v_add_f32_e32 v180, 1.0, v180
	v_add_f32_e32 v181, 1.0, v181
	v_rcp_f32_e32 v178, v178
	v_rcp_f32_e32 v179, v179
	v_rcp_f32_e32 v180, v180
	v_rcp_f32_e32 v181, v181
	v_mul_f32_e32 v32, v32, v178
	v_mul_f32_e32 v33, v33, v179
	v_mul_f32_e32 v34, v34, v180
	v_mul_f32_e32 v35, v35, v181
	v_cvt_pk_bf16_f32 v32, v32, v33
	v_cvt_pk_bf16_f32 v33, v34, v35
	ds_write_b64 v170, v[32:33] offset:4096
	v_mul_f32_e32 v178, 0xbfb8aa3b, v36
	v_mul_f32_e32 v179, 0xbfb8aa3b, v37
	v_mul_f32_e32 v180, 0xbfb8aa3b, v38
	v_mul_f32_e32 v181, 0xbfb8aa3b, v39
	v_exp_f32_e32 v178, v178
	v_exp_f32_e32 v179, v179
	v_exp_f32_e32 v180, v180
	v_exp_f32_e32 v181, v181
	v_add_f32_e32 v178, 1.0, v178
	v_add_f32_e32 v179, 1.0, v179
	v_add_f32_e32 v180, 1.0, v180
	v_add_f32_e32 v181, 1.0, v181
	v_rcp_f32_e32 v178, v178
	v_rcp_f32_e32 v179, v179
	v_rcp_f32_e32 v180, v180
	v_rcp_f32_e32 v181, v181
	v_mul_f32_e32 v36, v36, v178
	v_mul_f32_e32 v37, v37, v179
	v_mul_f32_e32 v38, v38, v180
	v_mul_f32_e32 v39, v39, v181
	v_cvt_pk_bf16_f32 v36, v36, v37
	v_cvt_pk_bf16_f32 v37, v38, v39
	ds_write_b64 v171, v[36:37] offset:4096
	v_mul_f32_e32 v178, 0xbfb8aa3b, v40
	v_mul_f32_e32 v179, 0xbfb8aa3b, v41
	v_mul_f32_e32 v180, 0xbfb8aa3b, v42
	v_mul_f32_e32 v181, 0xbfb8aa3b, v43
	v_exp_f32_e32 v178, v178
	v_exp_f32_e32 v179, v179
	v_exp_f32_e32 v180, v180
	v_exp_f32_e32 v181, v181
	v_add_f32_e32 v178, 1.0, v178
	v_add_f32_e32 v179, 1.0, v179
	v_add_f32_e32 v180, 1.0, v180
	v_add_f32_e32 v181, 1.0, v181
	v_rcp_f32_e32 v178, v178
	v_rcp_f32_e32 v179, v179
	v_rcp_f32_e32 v180, v180
	v_rcp_f32_e32 v181, v181
	v_mul_f32_e32 v40, v40, v178
	v_mul_f32_e32 v41, v41, v179
	v_mul_f32_e32 v42, v42, v180
	v_mul_f32_e32 v43, v43, v181
	v_cvt_pk_bf16_f32 v40, v40, v41
	v_cvt_pk_bf16_f32 v41, v42, v43
	ds_write_b64 v172, v[40:41] offset:4096
	v_mul_f32_e32 v178, 0xbfb8aa3b, v44
	v_mul_f32_e32 v179, 0xbfb8aa3b, v45
	v_mul_f32_e32 v180, 0xbfb8aa3b, v46
	v_mul_f32_e32 v181, 0xbfb8aa3b, v47
	v_exp_f32_e32 v178, v178
	v_exp_f32_e32 v179, v179
	v_exp_f32_e32 v180, v180
	v_exp_f32_e32 v181, v181
	v_add_f32_e32 v178, 1.0, v178
	v_add_f32_e32 v179, 1.0, v179
	v_add_f32_e32 v180, 1.0, v180
	v_add_f32_e32 v181, 1.0, v181
	v_rcp_f32_e32 v178, v178
	v_rcp_f32_e32 v179, v179
	v_rcp_f32_e32 v180, v180
	v_rcp_f32_e32 v181, v181
	v_mul_f32_e32 v44, v44, v178
	v_mul_f32_e32 v45, v45, v179
	v_mul_f32_e32 v46, v46, v180
	v_mul_f32_e32 v47, v47, v181
	v_cvt_pk_bf16_f32 v44, v44, v45
	v_cvt_pk_bf16_f32 v45, v46, v47
	ds_write_b64 v173, v[44:45] offset:4096
	v_mul_f32_e32 v178, 0xbfb8aa3b, v48
	v_mul_f32_e32 v179, 0xbfb8aa3b, v49
	v_mul_f32_e32 v180, 0xbfb8aa3b, v50
	v_mul_f32_e32 v181, 0xbfb8aa3b, v51
	v_exp_f32_e32 v178, v178
; DEV u16 f2bf(float f) { return (u16)(pack2(f, f) & 0xffffu); }
; DEV float silu_f(float x) { return x / (1.f + __expf(-x)); }
; DEV void phase_p1(const Params& p, int g, char* smem) {
;     ...
;         const bool dosilu = (n0 < 512) || (n0 >= 2048);
;         acc_foreach(acc, m0, n0, [&](int m, int n, float& v) {
;           const float o = dosilu ? silu_f(v) : v;
;           PHG[(size_t)m * 2560 + n] = f2bf(o);
;         });
	v_exp_f32_e32 v179, v179
	v_exp_f32_e32 v180, v180
	v_exp_f32_e32 v181, v181
	v_add_f32_e32 v178, 1.0, v178
	v_add_f32_e32 v179, 1.0, v179
	v_add_f32_e32 v180, 1.0, v180
	v_add_f32_e32 v181, 1.0, v181
	v_rcp_f32_e32 v178, v178
	v_rcp_f32_e32 v179, v179
	v_rcp_f32_e32 v180, v180
	v_rcp_f32_e32 v181, v181
	v_mul_f32_e32 v48, v48, v178
	v_mul_f32_e32 v49, v49, v179
	v_mul_f32_e32 v50, v50, v180
	v_mul_f32_e32 v51, v51, v181
	v_cvt_pk_bf16_f32 v48, v48, v49
	v_cvt_pk_bf16_f32 v49, v50, v51
	ds_write_b64 v170, v[48:49] offset:6144
	v_mul_f32_e32 v178, 0xbfb8aa3b, v52
	v_mul_f32_e32 v179, 0xbfb8aa3b, v53
	v_mul_f32_e32 v180, 0xbfb8aa3b, v54
	v_mul_f32_e32 v181, 0xbfb8aa3b, v55
	v_exp_f32_e32 v178, v178
	v_exp_f32_e32 v179, v179
	v_exp_f32_e32 v180, v180
	v_exp_f32_e32 v181, v181
	v_add_f32_e32 v178, 1.0, v178
	v_add_f32_e32 v179, 1.0, v179
	v_add_f32_e32 v180, 1.0, v180
	v_add_f32_e32 v181, 1.0, v181
	v_rcp_f32_e32 v178, v178
	v_rcp_f32_e32 v179, v179
	v_rcp_f32_e32 v180, v180
	v_rcp_f32_e32 v181, v181
	v_mul_f32_e32 v52, v52, v178
	v_mul_f32_e32 v53, v53, v179
	v_mul_f32_e32 v54, v54, v180
	v_mul_f32_e32 v55, v55, v181
	v_cvt_pk_bf16_f32 v52, v52, v53
	v_cvt_pk_bf16_f32 v53, v54, v55
	ds_write_b64 v171, v[52:53] offset:6144
	v_mul_f32_e32 v178, 0xbfb8aa3b, v56
	v_mul_f32_e32 v179, 0xbfb8aa3b, v57
	v_mul_f32_e32 v180, 0xbfb8aa3b, v58
	v_mul_f32_e32 v181, 0xbfb8aa3b, v59
	v_exp_f32_e32 v178, v178
	v_exp_f32_e32 v179, v179
	v_exp_f32_e32 v180, v180
	v_exp_f32_e32 v181, v181
	v_add_f32_e32 v178, 1.0, v178
	v_add_f32_e32 v179, 1.0, v179
	v_add_f32_e32 v180, 1.0, v180
	v_add_f32_e32 v181, 1.0, v181
	v_rcp_f32_e32 v178, v178
	v_rcp_f32_e32 v179, v179
	v_rcp_f32_e32 v180, v180
	v_rcp_f32_e32 v181, v181
	v_mul_f32_e32 v56, v56, v178
	v_mul_f32_e32 v57, v57, v179
	v_mul_f32_e32 v58, v58, v180
	v_mul_f32_e32 v59, v59, v181
	v_cvt_pk_bf16_f32 v56, v56, v57
	v_cvt_pk_bf16_f32 v57, v58, v59
	ds_write_b64 v172, v[56:57] offset:6144
	v_mul_f32_e32 v178, 0xbfb8aa3b, v60
	v_mul_f32_e32 v179, 0xbfb8aa3b, v61
	v_mul_f32_e32 v180, 0xbfb8aa3b, v62
	v_mul_f32_e32 v181, 0xbfb8aa3b, v63
	v_exp_f32_e32 v178, v178
	v_exp_f32_e32 v179, v179
	v_exp_f32_e32 v180, v180
	v_exp_f32_e32 v181, v181
	v_add_f32_e32 v178, 1.0, v178
	v_add_f32_e32 v179, 1.0, v179
	v_add_f32_e32 v180, 1.0, v180
	v_add_f32_e32 v181, 1.0, v181
	v_rcp_f32_e32 v178, v178
	v_rcp_f32_e32 v179, v179
	v_rcp_f32_e32 v180, v180
	v_rcp_f32_e32 v181, v181
	v_mul_f32_e32 v60, v60, v178
	v_mul_f32_e32 v61, v61, v179
	v_mul_f32_e32 v62, v62, v180
	v_mul_f32_e32 v63, v63, v181
	v_cvt_pk_bf16_f32 v60, v60, v61
	v_cvt_pk_bf16_f32 v61, v62, v63
	ds_write_b64 v173, v[60:61] offset:6144
	s_waitcnt lgkmcnt(0)
	ds_read_b128 v[32:35], v168
	ds_read_b128 v[36:39], v168 offset:1024
	ds_read_b128 v[40:43], v168 offset:2048
	ds_read_b128 v[44:47], v168 offset:3072
	ds_read_b128 v[48:51], v168 offset:4096
	ds_read_b128 v[52:55], v168 offset:5120
	ds_read_b128 v[56:59], v168 offset:6144
	ds_read_b128 v[60:63], v168 offset:7168
	s_waitcnt lgkmcnt(7)
	global_store_dwordx4 v169, v[32:35], s[56:57]
	v_add_u32_e32 v169, 0xa000, v169
	s_waitcnt lgkmcnt(6)
	global_store_dwordx4 v169, v[36:39], s[56:57]
	v_add_u32_e32 v169, 0xa000, v169
	s_waitcnt lgkmcnt(5)
	global_store_dwordx4 v169, v[40:43], s[56:57]
	v_add_u32_e32 v169, 0xa000, v169
	s_waitcnt lgkmcnt(4)
	global_store_dwordx4 v169, v[44:47], s[56:57]
	v_add_u32_e32 v169, 0xa000, v169
	s_waitcnt lgkmcnt(3)
	global_store_dwordx4 v169, v[48:51], s[56:57]
	v_add_u32_e32 v169, 0xa000, v169
	s_waitcnt lgkmcnt(2)
	global_store_dwordx4 v169, v[52:55], s[56:57]
	v_add_u32_e32 v169, 0xa000, v169
	s_waitcnt lgkmcnt(1)
	global_store_dwordx4 v169, v[56:59], s[56:57]
	v_add_u32_e32 v169, 0xa000, v169
	s_waitcnt lgkmcnt(0)
	global_store_dwordx4 v169, v[60:63], s[56:57]
	v_add_u32_e32 v169, 0xa000, v169
	v_mul_f32_e32 v178, 0xbfb8aa3b, v64
	v_mul_f32_e32 v179, 0xbfb8aa3b, v65
	v_mul_f32_e32 v180, 0xbfb8aa3b, v66
	v_mul_f32_e32 v181, 0xbfb8aa3b, v67
	v_exp_f32_e32 v178, v178
	v_exp_f32_e32 v179, v179
	v_exp_f32_e32 v180, v180
	v_exp_f32_e32 v181, v181
	v_add_f32_e32 v178, 1.0, v178
	v_add_f32_e32 v179, 1.0, v179
	v_add_f32_e32 v180, 1.0, v180
	v_add_f32_e32 v181, 1.0, v181
	v_rcp_f32_e32 v178, v178
	v_rcp_f32_e32 v179, v179
	v_rcp_f32_e32 v180, v180
	v_rcp_f32_e32 v181, v181
	v_mul_f32_e32 v64, v64, v178
	v_mul_f32_e32 v65, v65, v179
	v_mul_f32_e32 v66, v66, v180
	v_mul_f32_e32 v67, v67, v181
	v_cvt_pk_bf16_f32 v64, v64, v65
	v_cvt_pk_bf16_f32 v65, v66, v67
	ds_write_b64 v170, v[64:65]
	v_mul_f32_e32 v178, 0xbfb8aa3b, v68
	v_mul_f32_e32 v179, 0xbfb8aa3b, v69
	v_mul_f32_e32 v180, 0xbfb8aa3b, v70
	v_mul_f32_e32 v181, 0xbfb8aa3b, v71
	v_exp_f32_e32 v178, v178
	v_exp_f32_e32 v179, v179
	v_exp_f32_e32 v180, v180
	v_exp_f32_e32 v181, v181
	v_add_f32_e32 v178, 1.0, v178
	v_add_f32_e32 v179, 1.0, v179
	v_add_f32_e32 v180, 1.0, v180
	v_add_f32_e32 v181, 1.0, v181
	v_rcp_f32_e32 v178, v178
	v_rcp_f32_e32 v179, v179
	v_rcp_f32_e32 v180, v180
	v_rcp_f32_e32 v181, v181
	v_mul_f32_e32 v68, v68, v178
	v_mul_f32_e32 v69, v69, v179
	v_mul_f32_e32 v70, v70, v180
	v_mul_f32_e32 v71, v71, v181
	v_cvt_pk_bf16_f32 v68, v68, v69
	v_cvt_pk_bf16_f32 v69, v70, v71
	ds_write_b64 v171, v[68:69]
	v_mul_f32_e32 v178, 0xbfb8aa3b, v72
	v_mul_f32_e32 v179, 0xbfb8aa3b, v73
	v_mul_f32_e32 v180, 0xbfb8aa3b, v74
	v_mul_f32_e32 v181, 0xbfb8aa3b, v75
	v_exp_f32_e32 v178, v178
	v_exp_f32_e32 v179, v179
	v_exp_f32_e32 v180, v180
	v_exp_f32_e32 v181, v181
	v_add_f32_e32 v178, 1.0, v178
	v_add_f32_e32 v179, 1.0, v179
	v_add_f32_e32 v180, 1.0, v180
	v_add_f32_e32 v181, 1.0, v181
	v_rcp_f32_e32 v178, v178
	v_rcp_f32_e32 v179, v179
; DEV u16 f2bf(float f) { return (u16)(pack2(f, f) & 0xffffu); }
; DEV float silu_f(float x) { return x / (1.f + __expf(-x)); }
; DEV void phase_p1(const Params& p, int g, char* smem) {
;     ...
;         const bool dosilu = (n0 < 512) || (n0 >= 2048);
;         acc_foreach(acc, m0, n0, [&](int m, int n, float& v) {
;           const float o = dosilu ? silu_f(v) : v;
;           PHG[(size_t)m * 2560 + n] = f2bf(o);
;         });
	v_rcp_f32_e32 v180, v180
	v_rcp_f32_e32 v181, v181
	v_mul_f32_e32 v72, v72, v178
	v_mul_f32_e32 v73, v73, v179
	v_mul_f32_e32 v74, v74, v180
	v_mul_f32_e32 v75, v75, v181
	v_cvt_pk_bf16_f32 v72, v72, v73
	v_cvt_pk_bf16_f32 v73, v74, v75
	ds_write_b64 v172, v[72:73]
	v_mul_f32_e32 v178, 0xbfb8aa3b, v76
	v_mul_f32_e32 v179, 0xbfb8aa3b, v77
	v_mul_f32_e32 v180, 0xbfb8aa3b, v78
	v_mul_f32_e32 v181, 0xbfb8aa3b, v79
	v_exp_f32_e32 v178, v178
	v_exp_f32_e32 v179, v179
	v_exp_f32_e32 v180, v180
	v_exp_f32_e32 v181, v181
	v_add_f32_e32 v178, 1.0, v178
	v_add_f32_e32 v179, 1.0, v179
	v_add_f32_e32 v180, 1.0, v180
	v_add_f32_e32 v181, 1.0, v181
	v_rcp_f32_e32 v178, v178
	v_rcp_f32_e32 v179, v179
	v_rcp_f32_e32 v180, v180
	v_rcp_f32_e32 v181, v181
	v_mul_f32_e32 v76, v76, v178
	v_mul_f32_e32 v77, v77, v179
	v_mul_f32_e32 v78, v78, v180
	v_mul_f32_e32 v79, v79, v181
	v_cvt_pk_bf16_f32 v76, v76, v77
	v_cvt_pk_bf16_f32 v77, v78, v79
	ds_write_b64 v173, v[76:77]
	v_mul_f32_e32 v178, 0xbfb8aa3b, v80
	v_mul_f32_e32 v179, 0xbfb8aa3b, v81
	v_mul_f32_e32 v180, 0xbfb8aa3b, v82
	v_mul_f32_e32 v181, 0xbfb8aa3b, v83
	v_exp_f32_e32 v178, v178
	v_exp_f32_e32 v179, v179
	v_exp_f32_e32 v180, v180
	v_exp_f32_e32 v181, v181
	v_add_f32_e32 v178, 1.0, v178
	v_add_f32_e32 v179, 1.0, v179
	v_add_f32_e32 v180, 1.0, v180
	v_add_f32_e32 v181, 1.0, v181
	v_rcp_f32_e32 v178, v178
	v_rcp_f32_e32 v179, v179
	v_rcp_f32_e32 v180, v180
	v_rcp_f32_e32 v181, v181
	v_mul_f32_e32 v80, v80, v178
	v_mul_f32_e32 v81, v81, v179
	v_mul_f32_e32 v82, v82, v180
	v_mul_f32_e32 v83, v83, v181
	v_cvt_pk_bf16_f32 v80, v80, v81
	v_cvt_pk_bf16_f32 v81, v82, v83
	ds_write_b64 v170, v[80:81] offset:2048
	v_mul_f32_e32 v178, 0xbfb8aa3b, v84
	v_mul_f32_e32 v179, 0xbfb8aa3b, v85
	v_mul_f32_e32 v180, 0xbfb8aa3b, v86
	v_mul_f32_e32 v181, 0xbfb8aa3b, v87
	v_exp_f32_e32 v178, v178
	v_exp_f32_e32 v179, v179
	v_exp_f32_e32 v180, v180
	v_exp_f32_e32 v181, v181
	v_add_f32_e32 v178, 1.0, v178
	v_add_f32_e32 v179, 1.0, v179
	v_add_f32_e32 v180, 1.0, v180
	v_add_f32_e32 v181, 1.0, v181
	v_rcp_f32_e32 v178, v178
	v_rcp_f32_e32 v179, v179
	v_rcp_f32_e32 v180, v180
	v_rcp_f32_e32 v181, v181
	v_mul_f32_e32 v84, v84, v178
	v_mul_f32_e32 v85, v85, v179
	v_mul_f32_e32 v86, v86, v180
	v_mul_f32_e32 v87, v87, v181
	v_cvt_pk_bf16_f32 v84, v84, v85
	v_cvt_pk_bf16_f32 v85, v86, v87
	ds_write_b64 v171, v[84:85] offset:2048
	v_mul_f32_e32 v178, 0xbfb8aa3b, v88
	v_mul_f32_e32 v179, 0xbfb8aa3b, v89
	v_mul_f32_e32 v180, 0xbfb8aa3b, v90
	v_mul_f32_e32 v181, 0xbfb8aa3b, v91
	v_exp_f32_e32 v178, v178
	v_exp_f32_e32 v179, v179
	v_exp_f32_e32 v180, v180
	v_exp_f32_e32 v181, v181
	v_add_f32_e32 v178, 1.0, v178
	v_add_f32_e32 v179, 1.0, v179
	v_add_f32_e32 v180, 1.0, v180
	v_add_f32_e32 v181, 1.0, v181
	v_rcp_f32_e32 v178, v178
	v_rcp_f32_e32 v179, v179
	v_rcp_f32_e32 v180, v180
	v_rcp_f32_e32 v181, v181
	v_mul_f32_e32 v88, v88, v178
	v_mul_f32_e32 v89, v89, v179
	v_mul_f32_e32 v90, v90, v180
	v_mul_f32_e32 v91, v91, v181
	v_cvt_pk_bf16_f32 v88, v88, v89
	v_cvt_pk_bf16_f32 v89, v90, v91
	ds_write_b64 v172, v[88:89] offset:2048
	v_mul_f32_e32 v178, 0xbfb8aa3b, v92
	v_mul_f32_e32 v179, 0xbfb8aa3b, v93
	v_mul_f32_e32 v180, 0xbfb8aa3b, v94
	v_mul_f32_e32 v181, 0xbfb8aa3b, v95
	v_exp_f32_e32 v178, v178
	v_exp_f32_e32 v179, v179
	v_exp_f32_e32 v180, v180
	v_exp_f32_e32 v181, v181
	v_add_f32_e32 v178, 1.0, v178
	v_add_f32_e32 v179, 1.0, v179
	v_add_f32_e32 v180, 1.0, v180
	v_add_f32_e32 v181, 1.0, v181
	v_rcp_f32_e32 v178, v178
	v_rcp_f32_e32 v179, v179
	v_rcp_f32_e32 v180, v180
	v_rcp_f32_e32 v181, v181
	v_mul_f32_e32 v92, v92, v178
	v_mul_f32_e32 v93, v93, v179
	v_mul_f32_e32 v94, v94, v180
	v_mul_f32_e32 v95, v95, v181
	v_cvt_pk_bf16_f32 v92, v92, v93
	v_cvt_pk_bf16_f32 v93, v94, v95
	ds_write_b64 v173, v[92:93] offset:2048
	v_mul_f32_e32 v178, 0xbfb8aa3b, v96
	v_mul_f32_e32 v179, 0xbfb8aa3b, v97
	v_mul_f32_e32 v180, 0xbfb8aa3b, v98
	v_mul_f32_e32 v181, 0xbfb8aa3b, v99
	v_exp_f32_e32 v178, v178
	v_exp_f32_e32 v179, v179
	v_exp_f32_e32 v180, v180
	v_exp_f32_e32 v181, v181
	v_add_f32_e32 v178, 1.0, v178
	v_add_f32_e32 v179, 1.0, v179
	v_add_f32_e32 v180, 1.0, v180
	v_add_f32_e32 v181, 1.0, v181
	v_rcp_f32_e32 v178, v178
	v_rcp_f32_e32 v179, v179
	v_rcp_f32_e32 v180, v180
	v_rcp_f32_e32 v181, v181
	v_mul_f32_e32 v96, v96, v178
	v_mul_f32_e32 v97, v97, v179
	v_mul_f32_e32 v98, v98, v180
	v_mul_f32_e32 v99, v99, v181
	v_cvt_pk_bf16_f32 v96, v96, v97
	v_cvt_pk_bf16_f32 v97, v98, v99
	ds_write_b64 v170, v[96:97] offset:4096
	v_mul_f32_e32 v178, 0xbfb8aa3b, v100
	v_mul_f32_e32 v179, 0xbfb8aa3b, v101
	v_mul_f32_e32 v180, 0xbfb8aa3b, v102
	v_mul_f32_e32 v181, 0xbfb8aa3b, v103
	v_exp_f32_e32 v178, v178
	v_exp_f32_e32 v179, v179
	v_exp_f32_e32 v180, v180
	v_exp_f32_e32 v181, v181
	v_add_f32_e32 v178, 1.0, v178
	v_add_f32_e32 v179, 1.0, v179
	v_add_f32_e32 v180, 1.0, v180
	v_add_f32_e32 v181, 1.0, v181
	v_rcp_f32_e32 v178, v178
	v_rcp_f32_e32 v179, v179
	v_rcp_f32_e32 v180, v180
	v_rcp_f32_e32 v181, v181
	v_mul_f32_e32 v100, v100, v178
	v_mul_f32_e32 v101, v101, v179
	v_mul_f32_e32 v102, v102, v180
	v_mul_f32_e32 v103, v103, v181
	v_cvt_pk_bf16_f32 v100, v100, v101
	v_cvt_pk_bf16_f32 v101, v102, v103
	ds_write_b64 v171, v[100:101] offset:4096
	v_mul_f32_e32 v178, 0xbfb8aa3b, v104
	v_mul_f32_e32 v179, 0xbfb8aa3b, v105
	v_mul_f32_e32 v180, 0xbfb8aa3b, v106
	v_mul_f32_e32 v181, 0xbfb8aa3b, v107
	v_exp_f32_e32 v178, v178
	v_exp_f32_e32 v179, v179
	v_exp_f32_e32 v180, v180
	v_exp_f32_e32 v181, v181
	v_add_f32_e32 v178, 1.0, v178
	v_add_f32_e32 v179, 1.0, v179
	v_add_f32_e32 v180, 1.0, v180
	v_add_f32_e32 v181, 1.0, v181
	v_rcp_f32_e32 v178, v178
; DEV u16 f2bf(float f) { return (u16)(pack2(f, f) & 0xffffu); }
; DEV float silu_f(float x) { return x / (1.f + __expf(-x)); }
; DEV void phase_p1(const Params& p, int g, char* smem) {
;     ...
;         const bool dosilu = (n0 < 512) || (n0 >= 2048);
;         acc_foreach(acc, m0, n0, [&](int m, int n, float& v) {
;           const float o = dosilu ? silu_f(v) : v;
;           PHG[(size_t)m * 2560 + n] = f2bf(o);
;         });
	v_rcp_f32_e32 v179, v179
	v_rcp_f32_e32 v180, v180
	v_rcp_f32_e32 v181, v181
	v_mul_f32_e32 v104, v104, v178
	v_mul_f32_e32 v105, v105, v179
	v_mul_f32_e32 v106, v106, v180
	v_mul_f32_e32 v107, v107, v181
	v_cvt_pk_bf16_f32 v104, v104, v105
	v_cvt_pk_bf16_f32 v105, v106, v107
	ds_write_b64 v172, v[104:105] offset:4096
	v_mul_f32_e32 v178, 0xbfb8aa3b, v108
	v_mul_f32_e32 v179, 0xbfb8aa3b, v109
	v_mul_f32_e32 v180, 0xbfb8aa3b, v110
	v_mul_f32_e32 v181, 0xbfb8aa3b, v111
	v_exp_f32_e32 v178, v178
	v_exp_f32_e32 v179, v179
	v_exp_f32_e32 v180, v180
	v_exp_f32_e32 v181, v181
	v_add_f32_e32 v178, 1.0, v178
	v_add_f32_e32 v179, 1.0, v179
	v_add_f32_e32 v180, 1.0, v180
	v_add_f32_e32 v181, 1.0, v181
	v_rcp_f32_e32 v178, v178
	v_rcp_f32_e32 v179, v179
	v_rcp_f32_e32 v180, v180
	v_rcp_f32_e32 v181, v181
	v_mul_f32_e32 v108, v108, v178
	v_mul_f32_e32 v109, v109, v179
	v_mul_f32_e32 v110, v110, v180
	v_mul_f32_e32 v111, v111, v181
	v_cvt_pk_bf16_f32 v108, v108, v109
	v_cvt_pk_bf16_f32 v109, v110, v111
	ds_write_b64 v173, v[108:109] offset:4096
	v_mul_f32_e32 v178, 0xbfb8aa3b, v112
	v_mul_f32_e32 v179, 0xbfb8aa3b, v113
	v_mul_f32_e32 v180, 0xbfb8aa3b, v114
	v_mul_f32_e32 v181, 0xbfb8aa3b, v115
	v_exp_f32_e32 v178, v178
	v_exp_f32_e32 v179, v179
	v_exp_f32_e32 v180, v180
	v_exp_f32_e32 v181, v181
	v_add_f32_e32 v178, 1.0, v178
	v_add_f32_e32 v179, 1.0, v179
	v_add_f32_e32 v180, 1.0, v180
	v_add_f32_e32 v181, 1.0, v181
	v_rcp_f32_e32 v178, v178
	v_rcp_f32_e32 v179, v179
	v_rcp_f32_e32 v180, v180
	v_rcp_f32_e32 v181, v181
	v_mul_f32_e32 v112, v112, v178
	v_mul_f32_e32 v113, v113, v179
	v_mul_f32_e32 v114, v114, v180
	v_mul_f32_e32 v115, v115, v181
	v_cvt_pk_bf16_f32 v112, v112, v113
	v_cvt_pk_bf16_f32 v113, v114, v115
	ds_write_b64 v170, v[112:113] offset:6144
	v_mul_f32_e32 v178, 0xbfb8aa3b, v116
	v_mul_f32_e32 v179, 0xbfb8aa3b, v117
	v_mul_f32_e32 v180, 0xbfb8aa3b, v118
	v_mul_f32_e32 v181, 0xbfb8aa3b, v119
	v_exp_f32_e32 v178, v178
	v_exp_f32_e32 v179, v179
	v_exp_f32_e32 v180, v180
	v_exp_f32_e32 v181, v181
	v_add_f32_e32 v178, 1.0, v178
	v_add_f32_e32 v179, 1.0, v179
	v_add_f32_e32 v180, 1.0, v180
	v_add_f32_e32 v181, 1.0, v181
	v_rcp_f32_e32 v178, v178
	v_rcp_f32_e32 v179, v179
	v_rcp_f32_e32 v180, v180
	v_rcp_f32_e32 v181, v181
	v_mul_f32_e32 v116, v116, v178
	v_mul_f32_e32 v117, v117, v179
	v_mul_f32_e32 v118, v118, v180
	v_mul_f32_e32 v119, v119, v181
	v_cvt_pk_bf16_f32 v116, v116, v117
	v_cvt_pk_bf16_f32 v117, v118, v119
	ds_write_b64 v171, v[116:117] offset:6144
	v_mul_f32_e32 v178, 0xbfb8aa3b, v120
	v_mul_f32_e32 v179, 0xbfb8aa3b, v121
	v_mul_f32_e32 v180, 0xbfb8aa3b, v122
	v_mul_f32_e32 v181, 0xbfb8aa3b, v123
	v_exp_f32_e32 v178, v178
	v_exp_f32_e32 v179, v179
	v_exp_f32_e32 v180, v180
	v_exp_f32_e32 v181, v181
	v_add_f32_e32 v178, 1.0, v178
	v_add_f32_e32 v179, 1.0, v179
	v_add_f32_e32 v180, 1.0, v180
	v_add_f32_e32 v181, 1.0, v181
	v_rcp_f32_e32 v178, v178
	v_rcp_f32_e32 v179, v179
	v_rcp_f32_e32 v180, v180
	v_rcp_f32_e32 v181, v181
	v_mul_f32_e32 v120, v120, v178
	v_mul_f32_e32 v121, v121, v179
	v_mul_f32_e32 v122, v122, v180
	v_mul_f32_e32 v123, v123, v181
	v_cvt_pk_bf16_f32 v120, v120, v121
	v_cvt_pk_bf16_f32 v121, v122, v123
	ds_write_b64 v172, v[120:121] offset:6144
	v_mul_f32_e32 v178, 0xbfb8aa3b, v124
	v_mul_f32_e32 v179, 0xbfb8aa3b, v125
	v_mul_f32_e32 v180, 0xbfb8aa3b, v126
	v_mul_f32_e32 v181, 0xbfb8aa3b, v127
	v_exp_f32_e32 v178, v178
	v_exp_f32_e32 v179, v179
	v_exp_f32_e32 v180, v180
	v_exp_f32_e32 v181, v181
	v_add_f32_e32 v178, 1.0, v178
	v_add_f32_e32 v179, 1.0, v179
	v_add_f32_e32 v180, 1.0, v180
	v_add_f32_e32 v181, 1.0, v181
	v_rcp_f32_e32 v178, v178
	v_rcp_f32_e32 v179, v179
	v_rcp_f32_e32 v180, v180
	v_rcp_f32_e32 v181, v181
	v_mul_f32_e32 v124, v124, v178
	v_mul_f32_e32 v125, v125, v179
	v_mul_f32_e32 v126, v126, v180
	v_mul_f32_e32 v127, v127, v181
	v_cvt_pk_bf16_f32 v124, v124, v125
	v_cvt_pk_bf16_f32 v125, v126, v127
	ds_write_b64 v173, v[124:125] offset:6144
	s_waitcnt lgkmcnt(0)
	ds_read_b128 v[64:67], v168
	ds_read_b128 v[68:71], v168 offset:1024
	ds_read_b128 v[72:75], v168 offset:2048
	ds_read_b128 v[76:79], v168 offset:3072
	ds_read_b128 v[80:83], v168 offset:4096
	ds_read_b128 v[84:87], v168 offset:5120
	ds_read_b128 v[88:91], v168 offset:6144
	ds_read_b128 v[92:95], v168 offset:7168
	s_waitcnt lgkmcnt(7)
	global_store_dwordx4 v169, v[64:67], s[56:57]
	v_add_u32_e32 v169, 0xa000, v169
	s_waitcnt lgkmcnt(6)
	global_store_dwordx4 v169, v[68:71], s[56:57]
	v_add_u32_e32 v169, 0xa000, v169
	s_waitcnt lgkmcnt(5)
	global_store_dwordx4 v169, v[72:75], s[56:57]
	v_add_u32_e32 v169, 0xa000, v169
	s_waitcnt lgkmcnt(4)
	global_store_dwordx4 v169, v[76:79], s[56:57]
	v_add_u32_e32 v169, 0xa000, v169
	s_waitcnt lgkmcnt(3)
	global_store_dwordx4 v169, v[80:83], s[56:57]
	v_add_u32_e32 v169, 0xa000, v169
	s_waitcnt lgkmcnt(2)
	global_store_dwordx4 v169, v[84:87], s[56:57]
	v_add_u32_e32 v169, 0xa000, v169
	s_waitcnt lgkmcnt(1)
	global_store_dwordx4 v169, v[88:91], s[56:57]
	v_add_u32_e32 v169, 0xa000, v169
	s_waitcnt lgkmcnt(0)
	global_store_dwordx4 v169, v[92:95], s[56:57]
	v_add_u32_e32 v169, 0xa000, v169
	s_branch .LBB0_261
; DEV u16 f2bf(float f) { return (u16)(pack2(f, f) & 0xffffu); }
; DEV float sigmoid_f(float x) { return __builtin_amdgcn_rcpf(1.f + __expf(-x)); }
; DEV void phase_p1(const Params& p, int g, char* smem) {
;     ...
;       } else {
;         acc_foreach(acc, m0, n0, [&](int m, int n, float& v) { GT[(size_t)m * 2048 + (n - 2560)] = f2bf(sigmoid_f(v)); });
.Lp1a_gt:
	s_nop 7
	s_nop 7
	s_nop 3
	v_and_b32_e32 v160, 63, v202
	v_lshrrev_b32_e32 v161, 6, v202
	v_and_b32_e32 v164, 3, v161
	v_lshlrev_b32_e32 v164, 13, v164
	v_add_u32_e32 v164, 0x8000, v164
	v_lshrrev_b32_e32 v160, 2, v161
	v_lshl_add_u32 v164, v160, 16, v164
	v_and_b32_e32 v160, 63, v202
	v_and_b32_e32 v166, 15, v160
	v_lshrrev_b32_e32 v167, 4, v160
	v_lshl_add_u32 v168, v166, 7, v164
	v_and_b32_e32 v169, 1, v167
	v_lshl_add_u32 v168, v169, 3, v168
	v_lshrrev_b32_e32 v167, 1, v167
	v_and_b32_e32 v166, 7, v166
	v_xor_b32_e32 v166, v166, v167
	v_lshlrev_b32_e32 v166, 4, v166
	v_add_u32_e32 v170, v168, v166
	v_xor_b32_e32 v167, 0x20, v166
	v_add_u32_e32 v171, v168, v167
	v_xor_b32_e32 v167, 0x40, v166
	v_add_u32_e32 v172, v168, v167
	v_xor_b32_e32 v167, 0x60, v166
	v_add_u32_e32 v173, v168, v167
	v_and_b32_e32 v166, 31, v160
	v_lshrrev_b32_e32 v167, 5, v160
	v_lshlrev_b32_e32 v168, 7, v166
	v_lshl_add_u32 v168, v167, 3, v168
	v_add_u32_e32 v168, v164, v168
	v_and_b32_e32 v166, 7, v166
	v_lshlrev_b32_e32 v166, 4, v166
	v_lshrrev_b32_e32 v166, 3, v160
	v_and_b32_e32 v167, 7, v160
	v_lshrrev_b32_e32 v169, 2, v161
	v_lshl_add_u32 v169, v169, 7, v166
	v_add_u32_e32 v169, s5, v169
	v_mul_u32_u24_e32 v169, 0x1000, v169
	v_and_b32_e32 v168, 3, v161
	v_lshlrev_b32_e32 v168, 3, v168
	v_add_u32_e32 v168, v168, v167
	v_lshl_add_u32 v169, v168, 4, v169
	s_lshl_b32 s100, s4, 1
	s_sub_u32 s100, s100, 0x1400
	v_add_u32_e32 v169, s100, v169
	v_xor_b32_e32 v167, v166, v167
	v_lshlrev_b32_e32 v167, 4, v167
	v_lshl_add_u32 v168, v166, 7, v167
	v_add_u32_e32 v168, v164, v168
	v_mul_f32_e32 v0, 0xbfb8aa3b, v0
	v_mul_f32_e32 v1, 0xbfb8aa3b, v1
	v_mul_f32_e32 v2, 0xbfb8aa3b, v2
	v_mul_f32_e32 v3, 0xbfb8aa3b, v3
	v_exp_f32_e32 v0, v0
	v_exp_f32_e32 v1, v1
	v_exp_f32_e32 v2, v2
	v_exp_f32_e32 v3, v3
	v_add_f32_e32 v0, 1.0, v0
	v_add_f32_e32 v1, 1.0, v1
	v_add_f32_e32 v2, 1.0, v2
	v_add_f32_e32 v3, 1.0, v3
	v_rcp_f32_e32 v0, v0
	v_rcp_f32_e32 v1, v1
	v_rcp_f32_e32 v2, v2
	v_rcp_f32_e32 v3, v3
	v_cvt_pk_bf16_f32 v0, v0, v1
	v_cvt_pk_bf16_f32 v1, v2, v3
	ds_write_b64 v170, v[0:1]
	v_mul_f32_e32 v4, 0xbfb8aa3b, v4
	v_mul_f32_e32 v5, 0xbfb8aa3b, v5
	v_mul_f32_e32 v6, 0xbfb8aa3b, v6
	v_mul_f32_e32 v7, 0xbfb8aa3b, v7
	v_exp_f32_e32 v4, v4
	v_exp_f32_e32 v5, v5
	v_exp_f32_e32 v6, v6
	v_exp_f32_e32 v7, v7
	v_add_f32_e32 v4, 1.0, v4
	v_add_f32_e32 v5, 1.0, v5
	v_add_f32_e32 v6, 1.0, v6
	v_add_f32_e32 v7, 1.0, v7
	v_rcp_f32_e32 v4, v4
	v_rcp_f32_e32 v5, v5
	v_rcp_f32_e32 v6, v6
	v_rcp_f32_e32 v7, v7
	v_cvt_pk_bf16_f32 v4, v4, v5
	v_cvt_pk_bf16_f32 v5, v6, v7
	ds_write_b64 v171, v[4:5]
	v_mul_f32_e32 v8, 0xbfb8aa3b, v8
	v_mul_f32_e32 v9, 0xbfb8aa3b, v9
	v_mul_f32_e32 v10, 0xbfb8aa3b, v10
	v_mul_f32_e32 v11, 0xbfb8aa3b, v11
	v_exp_f32_e32 v8, v8
	v_exp_f32_e32 v9, v9
	v_exp_f32_e32 v10, v10
	v_exp_f32_e32 v11, v11
	v_add_f32_e32 v8, 1.0, v8
	v_add_f32_e32 v9, 1.0, v9
	v_add_f32_e32 v10, 1.0, v10
	v_add_f32_e32 v11, 1.0, v11
	v_rcp_f32_e32 v8, v8
	v_rcp_f32_e32 v9, v9
	v_rcp_f32_e32 v10, v10
	v_rcp_f32_e32 v11, v11
	v_cvt_pk_bf16_f32 v8, v8, v9
	v_cvt_pk_bf16_f32 v9, v10, v11
	ds_write_b64 v172, v[8:9]
	v_mul_f32_e32 v12, 0xbfb8aa3b, v12
	v_mul_f32_e32 v13, 0xbfb8aa3b, v13
	v_mul_f32_e32 v14, 0xbfb8aa3b, v14
	v_mul_f32_e32 v15, 0xbfb8aa3b, v15
	v_exp_f32_e32 v12, v12
	v_exp_f32_e32 v13, v13
	v_exp_f32_e32 v14, v14
	v_exp_f32_e32 v15, v15
	v_add_f32_e32 v12, 1.0, v12
	v_add_f32_e32 v13, 1.0, v13
	v_add_f32_e32 v14, 1.0, v14
	v_add_f32_e32 v15, 1.0, v15
	v_rcp_f32_e32 v12, v12
	v_rcp_f32_e32 v13, v13
	v_rcp_f32_e32 v14, v14
	v_rcp_f32_e32 v15, v15
	v_cvt_pk_bf16_f32 v12, v12, v13
	v_cvt_pk_bf16_f32 v13, v14, v15
	ds_write_b64 v173, v[12:13]
	v_mul_f32_e32 v16, 0xbfb8aa3b, v16
	v_mul_f32_e32 v17, 0xbfb8aa3b, v17
	v_mul_f32_e32 v18, 0xbfb8aa3b, v18
	v_mul_f32_e32 v19, 0xbfb8aa3b, v19
	v_exp_f32_e32 v16, v16
	v_exp_f32_e32 v17, v17
	v_exp_f32_e32 v18, v18
	v_exp_f32_e32 v19, v19
	v_add_f32_e32 v16, 1.0, v16
	v_add_f32_e32 v17, 1.0, v17
	v_add_f32_e32 v18, 1.0, v18
	v_add_f32_e32 v19, 1.0, v19
	v_rcp_f32_e32 v16, v16
	v_rcp_f32_e32 v17, v17
	v_rcp_f32_e32 v18, v18
	v_rcp_f32_e32 v19, v19
	v_cvt_pk_bf16_f32 v16, v16, v17
	v_cvt_pk_bf16_f32 v17, v18, v19
	ds_write_b64 v170, v[16:17] offset:2048
	v_mul_f32_e32 v20, 0xbfb8aa3b, v20
	v_mul_f32_e32 v21, 0xbfb8aa3b, v21
	v_mul_f32_e32 v22, 0xbfb8aa3b, v22
	v_mul_f32_e32 v23, 0xbfb8aa3b, v23
	v_exp_f32_e32 v20, v20
	v_exp_f32_e32 v21, v21
	v_exp_f32_e32 v22, v22
	v_exp_f32_e32 v23, v23
	v_add_f32_e32 v20, 1.0, v20
	v_add_f32_e32 v21, 1.0, v21
	v_add_f32_e32 v22, 1.0, v22
	v_add_f32_e32 v23, 1.0, v23
	v_rcp_f32_e32 v20, v20
	v_rcp_f32_e32 v21, v21
	v_rcp_f32_e32 v22, v22
	v_rcp_f32_e32 v23, v23
	v_cvt_pk_bf16_f32 v20, v20, v21
	v_cvt_pk_bf16_f32 v21, v22, v23
	ds_write_b64 v171, v[20:21] offset:2048
	v_mul_f32_e32 v24, 0xbfb8aa3b, v24
	v_mul_f32_e32 v25, 0xbfb8aa3b, v25
	v_mul_f32_e32 v26, 0xbfb8aa3b, v26
	v_mul_f32_e32 v27, 0xbfb8aa3b, v27
	v_exp_f32_e32 v24, v24
	v_exp_f32_e32 v25, v25
	v_exp_f32_e32 v26, v26
	v_exp_f32_e32 v27, v27
	v_add_f32_e32 v24, 1.0, v24
	v_add_f32_e32 v25, 1.0, v25
	v_add_f32_e32 v26, 1.0, v26
	v_add_f32_e32 v27, 1.0, v27
	v_rcp_f32_e32 v24, v24
	v_rcp_f32_e32 v25, v25
	v_rcp_f32_e32 v26, v26
	v_rcp_f32_e32 v27, v27
	v_cvt_pk_bf16_f32 v24, v24, v25
	v_cvt_pk_bf16_f32 v25, v26, v27
	ds_write_b64 v172, v[24:25] offset:2048
	v_mul_f32_e32 v28, 0xbfb8aa3b, v28
	v_mul_f32_e32 v29, 0xbfb8aa3b, v29
	v_mul_f32_e32 v30, 0xbfb8aa3b, v30
	v_mul_f32_e32 v31, 0xbfb8aa3b, v31
	v_exp_f32_e32 v28, v28
	v_exp_f32_e32 v29, v29
	v_exp_f32_e32 v30, v30
	v_exp_f32_e32 v31, v31
	v_add_f32_e32 v28, 1.0, v28
	v_add_f32_e32 v29, 1.0, v29
; DEV u16 f2bf(float f) { return (u16)(pack2(f, f) & 0xffffu); }
; DEV float sigmoid_f(float x) { return __builtin_amdgcn_rcpf(1.f + __expf(-x)); }
; DEV void phase_p1(const Params& p, int g, char* smem) {
;     ...
;       } else {
;         acc_foreach(acc, m0, n0, [&](int m, int n, float& v) { GT[(size_t)m * 2048 + (n - 2560)] = f2bf(sigmoid_f(v)); });
	v_add_f32_e32 v30, 1.0, v30
	v_add_f32_e32 v31, 1.0, v31
	v_rcp_f32_e32 v28, v28
	v_rcp_f32_e32 v29, v29
	v_rcp_f32_e32 v30, v30
	v_rcp_f32_e32 v31, v31
	v_cvt_pk_bf16_f32 v28, v28, v29
	v_cvt_pk_bf16_f32 v29, v30, v31
	ds_write_b64 v173, v[28:29] offset:2048
	v_mul_f32_e32 v32, 0xbfb8aa3b, v32
	v_mul_f32_e32 v33, 0xbfb8aa3b, v33
	v_mul_f32_e32 v34, 0xbfb8aa3b, v34
	v_mul_f32_e32 v35, 0xbfb8aa3b, v35
	v_exp_f32_e32 v32, v32
	v_exp_f32_e32 v33, v33
	v_exp_f32_e32 v34, v34
	v_exp_f32_e32 v35, v35
	v_add_f32_e32 v32, 1.0, v32
	v_add_f32_e32 v33, 1.0, v33
	v_add_f32_e32 v34, 1.0, v34
	v_add_f32_e32 v35, 1.0, v35
	v_rcp_f32_e32 v32, v32
	v_rcp_f32_e32 v33, v33
	v_rcp_f32_e32 v34, v34
	v_rcp_f32_e32 v35, v35
	v_cvt_pk_bf16_f32 v32, v32, v33
	v_cvt_pk_bf16_f32 v33, v34, v35
	ds_write_b64 v170, v[32:33] offset:4096
	v_mul_f32_e32 v36, 0xbfb8aa3b, v36
	v_mul_f32_e32 v37, 0xbfb8aa3b, v37
	v_mul_f32_e32 v38, 0xbfb8aa3b, v38
	v_mul_f32_e32 v39, 0xbfb8aa3b, v39
	v_exp_f32_e32 v36, v36
	v_exp_f32_e32 v37, v37
	v_exp_f32_e32 v38, v38
	v_exp_f32_e32 v39, v39
	v_add_f32_e32 v36, 1.0, v36
	v_add_f32_e32 v37, 1.0, v37
	v_add_f32_e32 v38, 1.0, v38
	v_add_f32_e32 v39, 1.0, v39
	v_rcp_f32_e32 v36, v36
	v_rcp_f32_e32 v37, v37
	v_rcp_f32_e32 v38, v38
	v_rcp_f32_e32 v39, v39
	v_cvt_pk_bf16_f32 v36, v36, v37
	v_cvt_pk_bf16_f32 v37, v38, v39
	ds_write_b64 v171, v[36:37] offset:4096
	v_mul_f32_e32 v40, 0xbfb8aa3b, v40
	v_mul_f32_e32 v41, 0xbfb8aa3b, v41
	v_mul_f32_e32 v42, 0xbfb8aa3b, v42
	v_mul_f32_e32 v43, 0xbfb8aa3b, v43
	v_exp_f32_e32 v40, v40
	v_exp_f32_e32 v41, v41
	v_exp_f32_e32 v42, v42
	v_exp_f32_e32 v43, v43
	v_add_f32_e32 v40, 1.0, v40
	v_add_f32_e32 v41, 1.0, v41
	v_add_f32_e32 v42, 1.0, v42
	v_add_f32_e32 v43, 1.0, v43
	v_rcp_f32_e32 v40, v40
	v_rcp_f32_e32 v41, v41
	v_rcp_f32_e32 v42, v42
	v_rcp_f32_e32 v43, v43
	v_cvt_pk_bf16_f32 v40, v40, v41
	v_cvt_pk_bf16_f32 v41, v42, v43
	ds_write_b64 v172, v[40:41] offset:4096
	v_mul_f32_e32 v44, 0xbfb8aa3b, v44
	v_mul_f32_e32 v45, 0xbfb8aa3b, v45
	v_mul_f32_e32 v46, 0xbfb8aa3b, v46
	v_mul_f32_e32 v47, 0xbfb8aa3b, v47
	v_exp_f32_e32 v44, v44
	v_exp_f32_e32 v45, v45
	v_exp_f32_e32 v46, v46
	v_exp_f32_e32 v47, v47
	v_add_f32_e32 v44, 1.0, v44
	v_add_f32_e32 v45, 1.0, v45
	v_add_f32_e32 v46, 1.0, v46
	v_add_f32_e32 v47, 1.0, v47
	v_rcp_f32_e32 v44, v44
	v_rcp_f32_e32 v45, v45
	v_rcp_f32_e32 v46, v46
	v_rcp_f32_e32 v47, v47
	v_cvt_pk_bf16_f32 v44, v44, v45
	v_cvt_pk_bf16_f32 v45, v46, v47
	ds_write_b64 v173, v[44:45] offset:4096
	v_mul_f32_e32 v48, 0xbfb8aa3b, v48
	v_mul_f32_e32 v49, 0xbfb8aa3b, v49
	v_mul_f32_e32 v50, 0xbfb8aa3b, v50
	v_mul_f32_e32 v51, 0xbfb8aa3b, v51
	v_exp_f32_e32 v48, v48
	v_exp_f32_e32 v49, v49
	v_exp_f32_e32 v50, v50
	v_exp_f32_e32 v51, v51
	v_add_f32_e32 v48, 1.0, v48
	v_add_f32_e32 v49, 1.0, v49
	v_add_f32_e32 v50, 1.0, v50
	v_add_f32_e32 v51, 1.0, v51
	v_rcp_f32_e32 v48, v48
	v_rcp_f32_e32 v49, v49
	v_rcp_f32_e32 v50, v50
	v_rcp_f32_e32 v51, v51
	v_cvt_pk_bf16_f32 v48, v48, v49
	v_cvt_pk_bf16_f32 v49, v50, v51
	ds_write_b64 v170, v[48:49] offset:6144
	v_mul_f32_e32 v52, 0xbfb8aa3b, v52
	v_mul_f32_e32 v53, 0xbfb8aa3b, v53
	v_mul_f32_e32 v54, 0xbfb8aa3b, v54
	v_mul_f32_e32 v55, 0xbfb8aa3b, v55
	v_exp_f32_e32 v52, v52
	v_exp_f32_e32 v53, v53
	v_exp_f32_e32 v54, v54
	v_exp_f32_e32 v55, v55
	v_add_f32_e32 v52, 1.0, v52
	v_add_f32_e32 v53, 1.0, v53
	v_add_f32_e32 v54, 1.0, v54
	v_add_f32_e32 v55, 1.0, v55
	v_rcp_f32_e32 v52, v52
	v_rcp_f32_e32 v53, v53
	v_rcp_f32_e32 v54, v54
	v_rcp_f32_e32 v55, v55
	v_cvt_pk_bf16_f32 v52, v52, v53
	v_cvt_pk_bf16_f32 v53, v54, v55
	ds_write_b64 v171, v[52:53] offset:6144
	v_mul_f32_e32 v56, 0xbfb8aa3b, v56
	v_mul_f32_e32 v57, 0xbfb8aa3b, v57
	v_mul_f32_e32 v58, 0xbfb8aa3b, v58
	v_mul_f32_e32 v59, 0xbfb8aa3b, v59
	v_exp_f32_e32 v56, v56
	v_exp_f32_e32 v57, v57
	v_exp_f32_e32 v58, v58
	v_exp_f32_e32 v59, v59
	v_add_f32_e32 v56, 1.0, v56
	v_add_f32_e32 v57, 1.0, v57
	v_add_f32_e32 v58, 1.0, v58
	v_add_f32_e32 v59, 1.0, v59
	v_rcp_f32_e32 v56, v56
	v_rcp_f32_e32 v57, v57
	v_rcp_f32_e32 v58, v58
	v_rcp_f32_e32 v59, v59
	v_cvt_pk_bf16_f32 v56, v56, v57
	v_cvt_pk_bf16_f32 v57, v58, v59
	ds_write_b64 v172, v[56:57] offset:6144
	v_mul_f32_e32 v60, 0xbfb8aa3b, v60
	v_mul_f32_e32 v61, 0xbfb8aa3b, v61
	v_mul_f32_e32 v62, 0xbfb8aa3b, v62
	v_mul_f32_e32 v63, 0xbfb8aa3b, v63
	v_exp_f32_e32 v60, v60
	v_exp_f32_e32 v61, v61
	v_exp_f32_e32 v62, v62
	v_exp_f32_e32 v63, v63
	v_add_f32_e32 v60, 1.0, v60
	v_add_f32_e32 v61, 1.0, v61
	v_add_f32_e32 v62, 1.0, v62
	v_add_f32_e32 v63, 1.0, v63
	v_rcp_f32_e32 v60, v60
	v_rcp_f32_e32 v61, v61
	v_rcp_f32_e32 v62, v62
	v_rcp_f32_e32 v63, v63
	v_cvt_pk_bf16_f32 v60, v60, v61
	v_cvt_pk_bf16_f32 v61, v62, v63
	ds_write_b64 v173, v[60:61] offset:6144
	s_waitcnt lgkmcnt(0)
	ds_read_b128 v[32:35], v168
	ds_read_b128 v[36:39], v168 offset:1024
	ds_read_b128 v[40:43], v168 offset:2048
	ds_read_b128 v[44:47], v168 offset:3072
	ds_read_b128 v[48:51], v168 offset:4096
	ds_read_b128 v[52:55], v168 offset:5120
	ds_read_b128 v[56:59], v168 offset:6144
	ds_read_b128 v[60:63], v168 offset:7168
	s_waitcnt lgkmcnt(7)
	global_store_dwordx4 v169, v[32:35], s[20:21]
	v_add_u32_e32 v169, 0x8000, v169
	s_waitcnt lgkmcnt(6)
	global_store_dwordx4 v169, v[36:39], s[20:21]
	v_add_u32_e32 v169, 0x8000, v169
	s_waitcnt lgkmcnt(5)
	global_store_dwordx4 v169, v[40:43], s[20:21]
	v_add_u32_e32 v169, 0x8000, v169
	s_waitcnt lgkmcnt(4)
	global_store_dwordx4 v169, v[44:47], s[20:21]
	v_add_u32_e32 v169, 0x8000, v169
	s_waitcnt lgkmcnt(3)
	global_store_dwordx4 v169, v[48:51], s[20:21]
	v_add_u32_e32 v169, 0x8000, v169
	s_waitcnt lgkmcnt(2)
; DEV u16 f2bf(float f) { return (u16)(pack2(f, f) & 0xffffu); }
; DEV float sigmoid_f(float x) { return __builtin_amdgcn_rcpf(1.f + __expf(-x)); }
; DEV void phase_p1(const Params& p, int g, char* smem) {
;     ...
;       } else {
;         acc_foreach(acc, m0, n0, [&](int m, int n, float& v) { GT[(size_t)m * 2048 + (n - 2560)] = f2bf(sigmoid_f(v)); });
	global_store_dwordx4 v169, v[52:55], s[20:21]
	v_add_u32_e32 v169, 0x8000, v169
	s_waitcnt lgkmcnt(1)
	global_store_dwordx4 v169, v[56:59], s[20:21]
	v_add_u32_e32 v169, 0x8000, v169
	s_waitcnt lgkmcnt(0)
	global_store_dwordx4 v169, v[60:63], s[20:21]
	v_add_u32_e32 v169, 0x8000, v169
	v_mul_f32_e32 v64, 0xbfb8aa3b, v64
	v_mul_f32_e32 v65, 0xbfb8aa3b, v65
	v_mul_f32_e32 v66, 0xbfb8aa3b, v66
	v_mul_f32_e32 v67, 0xbfb8aa3b, v67
	v_exp_f32_e32 v64, v64
	v_exp_f32_e32 v65, v65
	v_exp_f32_e32 v66, v66
	v_exp_f32_e32 v67, v67
	v_add_f32_e32 v64, 1.0, v64
	v_add_f32_e32 v65, 1.0, v65
	v_add_f32_e32 v66, 1.0, v66
	v_add_f32_e32 v67, 1.0, v67
	v_rcp_f32_e32 v64, v64
	v_rcp_f32_e32 v65, v65
	v_rcp_f32_e32 v66, v66
	v_rcp_f32_e32 v67, v67
	v_cvt_pk_bf16_f32 v64, v64, v65
	v_cvt_pk_bf16_f32 v65, v66, v67
	ds_write_b64 v170, v[64:65]
	v_mul_f32_e32 v68, 0xbfb8aa3b, v68
	v_mul_f32_e32 v69, 0xbfb8aa3b, v69
	v_mul_f32_e32 v70, 0xbfb8aa3b, v70
	v_mul_f32_e32 v71, 0xbfb8aa3b, v71
	v_exp_f32_e32 v68, v68
	v_exp_f32_e32 v69, v69
	v_exp_f32_e32 v70, v70
	v_exp_f32_e32 v71, v71
	v_add_f32_e32 v68, 1.0, v68
	v_add_f32_e32 v69, 1.0, v69
	v_add_f32_e32 v70, 1.0, v70
	v_add_f32_e32 v71, 1.0, v71
	v_rcp_f32_e32 v68, v68
	v_rcp_f32_e32 v69, v69
	v_rcp_f32_e32 v70, v70
	v_rcp_f32_e32 v71, v71
	v_cvt_pk_bf16_f32 v68, v68, v69
	v_cvt_pk_bf16_f32 v69, v70, v71
	ds_write_b64 v171, v[68:69]
	v_mul_f32_e32 v72, 0xbfb8aa3b, v72
	v_mul_f32_e32 v73, 0xbfb8aa3b, v73
	v_mul_f32_e32 v74, 0xbfb8aa3b, v74
	v_mul_f32_e32 v75, 0xbfb8aa3b, v75
	v_exp_f32_e32 v72, v72
	v_exp_f32_e32 v73, v73
	v_exp_f32_e32 v74, v74
	v_exp_f32_e32 v75, v75
	v_add_f32_e32 v72, 1.0, v72
	v_add_f32_e32 v73, 1.0, v73
	v_add_f32_e32 v74, 1.0, v74
	v_add_f32_e32 v75, 1.0, v75
	v_rcp_f32_e32 v72, v72
	v_rcp_f32_e32 v73, v73
	v_rcp_f32_e32 v74, v74
	v_rcp_f32_e32 v75, v75
	v_cvt_pk_bf16_f32 v72, v72, v73
	v_cvt_pk_bf16_f32 v73, v74, v75
	ds_write_b64 v172, v[72:73]
	v_mul_f32_e32 v76, 0xbfb8aa3b, v76
	v_mul_f32_e32 v77, 0xbfb8aa3b, v77
	v_mul_f32_e32 v78, 0xbfb8aa3b, v78
	v_mul_f32_e32 v79, 0xbfb8aa3b, v79
	v_exp_f32_e32 v76, v76
	v_exp_f32_e32 v77, v77
	v_exp_f32_e32 v78, v78
	v_exp_f32_e32 v79, v79
	v_add_f32_e32 v76, 1.0, v76
	v_add_f32_e32 v77, 1.0, v77
	v_add_f32_e32 v78, 1.0, v78
	v_add_f32_e32 v79, 1.0, v79
	v_rcp_f32_e32 v76, v76
	v_rcp_f32_e32 v77, v77
	v_rcp_f32_e32 v78, v78
	v_rcp_f32_e32 v79, v79
	v_cvt_pk_bf16_f32 v76, v76, v77
	v_cvt_pk_bf16_f32 v77, v78, v79
	ds_write_b64 v173, v[76:77]
	v_mul_f32_e32 v80, 0xbfb8aa3b, v80
	v_mul_f32_e32 v81, 0xbfb8aa3b, v81
	v_mul_f32_e32 v82, 0xbfb8aa3b, v82
	v_mul_f32_e32 v83, 0xbfb8aa3b, v83
	v_exp_f32_e32 v80, v80
	v_exp_f32_e32 v81, v81
	v_exp_f32_e32 v82, v82
	v_exp_f32_e32 v83, v83
	v_add_f32_e32 v80, 1.0, v80
	v_add_f32_e32 v81, 1.0, v81
	v_add_f32_e32 v82, 1.0, v82
	v_add_f32_e32 v83, 1.0, v83
	v_rcp_f32_e32 v80, v80
	v_rcp_f32_e32 v81, v81
	v_rcp_f32_e32 v82, v82
	v_rcp_f32_e32 v83, v83
	v_cvt_pk_bf16_f32 v80, v80, v81
	v_cvt_pk_bf16_f32 v81, v82, v83
	ds_write_b64 v170, v[80:81] offset:2048
	v_mul_f32_e32 v84, 0xbfb8aa3b, v84
	v_mul_f32_e32 v85, 0xbfb8aa3b, v85
	v_mul_f32_e32 v86, 0xbfb8aa3b, v86
	v_mul_f32_e32 v87, 0xbfb8aa3b, v87
	v_exp_f32_e32 v84, v84
	v_exp_f32_e32 v85, v85
	v_exp_f32_e32 v86, v86
	v_exp_f32_e32 v87, v87
	v_add_f32_e32 v84, 1.0, v84
	v_add_f32_e32 v85, 1.0, v85
	v_add_f32_e32 v86, 1.0, v86
	v_add_f32_e32 v87, 1.0, v87
	v_rcp_f32_e32 v84, v84
	v_rcp_f32_e32 v85, v85
	v_rcp_f32_e32 v86, v86
	v_rcp_f32_e32 v87, v87
	v_cvt_pk_bf16_f32 v84, v84, v85
	v_cvt_pk_bf16_f32 v85, v86, v87
	ds_write_b64 v171, v[84:85] offset:2048
	v_mul_f32_e32 v88, 0xbfb8aa3b, v88
	v_mul_f32_e32 v89, 0xbfb8aa3b, v89
	v_mul_f32_e32 v90, 0xbfb8aa3b, v90
	v_mul_f32_e32 v91, 0xbfb8aa3b, v91
	v_exp_f32_e32 v88, v88
	v_exp_f32_e32 v89, v89
	v_exp_f32_e32 v90, v90
	v_exp_f32_e32 v91, v91
	v_add_f32_e32 v88, 1.0, v88
	v_add_f32_e32 v89, 1.0, v89
	v_add_f32_e32 v90, 1.0, v90
	v_add_f32_e32 v91, 1.0, v91
	v_rcp_f32_e32 v88, v88
	v_rcp_f32_e32 v89, v89
	v_rcp_f32_e32 v90, v90
	v_rcp_f32_e32 v91, v91
	v_cvt_pk_bf16_f32 v88, v88, v89
	v_cvt_pk_bf16_f32 v89, v90, v91
	ds_write_b64 v172, v[88:89] offset:2048
	v_mul_f32_e32 v92, 0xbfb8aa3b, v92
	v_mul_f32_e32 v93, 0xbfb8aa3b, v93
	v_mul_f32_e32 v94, 0xbfb8aa3b, v94
	v_mul_f32_e32 v95, 0xbfb8aa3b, v95
	v_exp_f32_e32 v92, v92
	v_exp_f32_e32 v93, v93
	v_exp_f32_e32 v94, v94
	v_exp_f32_e32 v95, v95
	v_add_f32_e32 v92, 1.0, v92
	v_add_f32_e32 v93, 1.0, v93
	v_add_f32_e32 v94, 1.0, v94
	v_add_f32_e32 v95, 1.0, v95
	v_rcp_f32_e32 v92, v92
	v_rcp_f32_e32 v93, v93
	v_rcp_f32_e32 v94, v94
	v_rcp_f32_e32 v95, v95
	v_cvt_pk_bf16_f32 v92, v92, v93
	v_cvt_pk_bf16_f32 v93, v94, v95
	ds_write_b64 v173, v[92:93] offset:2048
	v_mul_f32_e32 v96, 0xbfb8aa3b, v96
	v_mul_f32_e32 v97, 0xbfb8aa3b, v97
	v_mul_f32_e32 v98, 0xbfb8aa3b, v98
	v_mul_f32_e32 v99, 0xbfb8aa3b, v99
	v_exp_f32_e32 v96, v96
	v_exp_f32_e32 v97, v97
	v_exp_f32_e32 v98, v98
	v_exp_f32_e32 v99, v99
	v_add_f32_e32 v96, 1.0, v96
	v_add_f32_e32 v97, 1.0, v97
	v_add_f32_e32 v98, 1.0, v98
	v_add_f32_e32 v99, 1.0, v99
	v_rcp_f32_e32 v96, v96
	v_rcp_f32_e32 v97, v97
	v_rcp_f32_e32 v98, v98
	v_rcp_f32_e32 v99, v99
	v_cvt_pk_bf16_f32 v96, v96, v97
	v_cvt_pk_bf16_f32 v97, v98, v99
	ds_write_b64 v170, v[96:97] offset:4096
	v_mul_f32_e32 v100, 0xbfb8aa3b, v100
; DEV u16 f2bf(float f) { return (u16)(pack2(f, f) & 0xffffu); }
; DEV float silu_f(float x) { return x / (1.f + __expf(-x)); }
; DEV float sigmoid_f(float x) { return __builtin_amdgcn_rcpf(1.f + __expf(-x)); }
; template <class F>
; DEV void acc_foreach(Acc& acc, int m0, int n0, F f) {
;   asm volatile("s_nop 7\n\ts_nop 7\n\ts_nop 3" ::: "memory");
;   const int tid = tidx_full();
;   const int wave = tid >> 6, lane = tid & 63;
;   const int wm = (wave >> 2) * 128, wn = (wave & 3) * 64;
;   const int lr = lane & 31, lh = lane >> 5;
; #pragma unroll
;   for (int i = 0; i < 4; ++i)
; #pragma unroll
;     for (int j = 0; j < 2; ++j)
; #pragma unroll
;       for (int r = 0; r < 16; ++r) {
;         const int m = m0 + wm + 32 * i + (r & 3) + 8 * (r >> 2) + 4 * lh;
;         const int n = n0 + wn + 32 * j + lr;
;         float v = acc[i][j][r];
;         f(m, n, v);
;         acc[i][j][r] = v;
;       }
; DEV void phase_p1(const Params& p, int g, char* smem) {
;     ...
;         acc_foreach(acc, m0, n0, [&](int m, int n, float& v) {
;           const float o = dosilu ? silu_f(v) : v;
;           PHG[(size_t)m * 2560 + n] = f2bf(o);
;         });
;       } else {
;         acc_foreach(acc, m0, n0, [&](int m, int n, float& v) { GT[(size_t)m * 2048 + (n - 2560)] = f2bf(sigmoid_f(v)); });
	v_mul_f32_e32 v101, 0xbfb8aa3b, v101
	v_mul_f32_e32 v102, 0xbfb8aa3b, v102
	v_mul_f32_e32 v103, 0xbfb8aa3b, v103
	v_exp_f32_e32 v100, v100
	v_exp_f32_e32 v101, v101
	v_exp_f32_e32 v102, v102
	v_exp_f32_e32 v103, v103
	v_add_f32_e32 v100, 1.0, v100
	v_add_f32_e32 v101, 1.0, v101
	v_add_f32_e32 v102, 1.0, v102
	v_add_f32_e32 v103, 1.0, v103
	v_rcp_f32_e32 v100, v100
	v_rcp_f32_e32 v101, v101
	v_rcp_f32_e32 v102, v102
	v_rcp_f32_e32 v103, v103
	v_cvt_pk_bf16_f32 v100, v100, v101
	v_cvt_pk_bf16_f32 v101, v102, v103
	ds_write_b64 v171, v[100:101] offset:4096
	v_mul_f32_e32 v104, 0xbfb8aa3b, v104
	v_mul_f32_e32 v105, 0xbfb8aa3b, v105
	v_mul_f32_e32 v106, 0xbfb8aa3b, v106
	v_mul_f32_e32 v107, 0xbfb8aa3b, v107
	v_exp_f32_e32 v104, v104
	v_exp_f32_e32 v105, v105
	v_exp_f32_e32 v106, v106
	v_exp_f32_e32 v107, v107
	v_add_f32_e32 v104, 1.0, v104
	v_add_f32_e32 v105, 1.0, v105
	v_add_f32_e32 v106, 1.0, v106
	v_add_f32_e32 v107, 1.0, v107
	v_rcp_f32_e32 v104, v104
	v_rcp_f32_e32 v105, v105
	v_rcp_f32_e32 v106, v106
	v_rcp_f32_e32 v107, v107
	v_cvt_pk_bf16_f32 v104, v104, v105
	v_cvt_pk_bf16_f32 v105, v106, v107
	ds_write_b64 v172, v[104:105] offset:4096
	v_mul_f32_e32 v108, 0xbfb8aa3b, v108
	v_mul_f32_e32 v109, 0xbfb8aa3b, v109
	v_mul_f32_e32 v110, 0xbfb8aa3b, v110
	v_mul_f32_e32 v111, 0xbfb8aa3b, v111
	v_exp_f32_e32 v108, v108
	v_exp_f32_e32 v109, v109
	v_exp_f32_e32 v110, v110
	v_exp_f32_e32 v111, v111
	v_add_f32_e32 v108, 1.0, v108
	v_add_f32_e32 v109, 1.0, v109
	v_add_f32_e32 v110, 1.0, v110
	v_add_f32_e32 v111, 1.0, v111
	v_rcp_f32_e32 v108, v108
	v_rcp_f32_e32 v109, v109
	v_rcp_f32_e32 v110, v110
	v_rcp_f32_e32 v111, v111
	v_cvt_pk_bf16_f32 v108, v108, v109
	v_cvt_pk_bf16_f32 v109, v110, v111
	ds_write_b64 v173, v[108:109] offset:4096
	v_mul_f32_e32 v112, 0xbfb8aa3b, v112
	v_mul_f32_e32 v113, 0xbfb8aa3b, v113
	v_mul_f32_e32 v114, 0xbfb8aa3b, v114
	v_mul_f32_e32 v115, 0xbfb8aa3b, v115
	v_exp_f32_e32 v112, v112
	v_exp_f32_e32 v113, v113
	v_exp_f32_e32 v114, v114
	v_exp_f32_e32 v115, v115
	v_add_f32_e32 v112, 1.0, v112
	v_add_f32_e32 v113, 1.0, v113
	v_add_f32_e32 v114, 1.0, v114
	v_add_f32_e32 v115, 1.0, v115
	v_rcp_f32_e32 v112, v112
	v_rcp_f32_e32 v113, v113
	v_rcp_f32_e32 v114, v114
	v_rcp_f32_e32 v115, v115
	v_cvt_pk_bf16_f32 v112, v112, v113
	v_cvt_pk_bf16_f32 v113, v114, v115
	ds_write_b64 v170, v[112:113] offset:6144
	v_mul_f32_e32 v116, 0xbfb8aa3b, v116
	v_mul_f32_e32 v117, 0xbfb8aa3b, v117
	v_mul_f32_e32 v118, 0xbfb8aa3b, v118
	v_mul_f32_e32 v119, 0xbfb8aa3b, v119
	v_exp_f32_e32 v116, v116
	v_exp_f32_e32 v117, v117
	v_exp_f32_e32 v118, v118
	v_exp_f32_e32 v119, v119
	v_add_f32_e32 v116, 1.0, v116
	v_add_f32_e32 v117, 1.0, v117
	v_add_f32_e32 v118, 1.0, v118
	v_add_f32_e32 v119, 1.0, v119
	v_rcp_f32_e32 v116, v116
	v_rcp_f32_e32 v117, v117
	v_rcp_f32_e32 v118, v118
	v_rcp_f32_e32 v119, v119
	v_cvt_pk_bf16_f32 v116, v116, v117
	v_cvt_pk_bf16_f32 v117, v118, v119
	ds_write_b64 v171, v[116:117] offset:6144
	v_mul_f32_e32 v120, 0xbfb8aa3b, v120
	v_mul_f32_e32 v121, 0xbfb8aa3b, v121
	v_mul_f32_e32 v122, 0xbfb8aa3b, v122
	v_mul_f32_e32 v123, 0xbfb8aa3b, v123
	v_exp_f32_e32 v120, v120
	v_exp_f32_e32 v121, v121
	v_exp_f32_e32 v122, v122
	v_exp_f32_e32 v123, v123
	v_add_f32_e32 v120, 1.0, v120
	v_add_f32_e32 v121, 1.0, v121
	v_add_f32_e32 v122, 1.0, v122
	v_add_f32_e32 v123, 1.0, v123
	v_rcp_f32_e32 v120, v120
	v_rcp_f32_e32 v121, v121
	v_rcp_f32_e32 v122, v122
	v_rcp_f32_e32 v123, v123
	v_cvt_pk_bf16_f32 v120, v120, v121
	v_cvt_pk_bf16_f32 v121, v122, v123
	ds_write_b64 v172, v[120:121] offset:6144
	v_mul_f32_e32 v124, 0xbfb8aa3b, v124
	v_mul_f32_e32 v125, 0xbfb8aa3b, v125
	v_mul_f32_e32 v126, 0xbfb8aa3b, v126
	v_mul_f32_e32 v127, 0xbfb8aa3b, v127
	v_exp_f32_e32 v124, v124
	v_exp_f32_e32 v125, v125
	v_exp_f32_e32 v126, v126
	v_exp_f32_e32 v127, v127
	v_add_f32_e32 v124, 1.0, v124
	v_add_f32_e32 v125, 1.0, v125
	v_add_f32_e32 v126, 1.0, v126
	v_add_f32_e32 v127, 1.0, v127
	v_rcp_f32_e32 v124, v124
	v_rcp_f32_e32 v125, v125
	v_rcp_f32_e32 v126, v126
	v_rcp_f32_e32 v127, v127
	v_cvt_pk_bf16_f32 v124, v124, v125
	v_cvt_pk_bf16_f32 v125, v126, v127
	ds_write_b64 v173, v[124:125] offset:6144
	s_waitcnt lgkmcnt(0)
	ds_read_b128 v[64:67], v168
	ds_read_b128 v[68:71], v168 offset:1024
	ds_read_b128 v[72:75], v168 offset:2048
	ds_read_b128 v[76:79], v168 offset:3072
	ds_read_b128 v[80:83], v168 offset:4096
	ds_read_b128 v[84:87], v168 offset:5120
	ds_read_b128 v[88:91], v168 offset:6144
	ds_read_b128 v[92:95], v168 offset:7168
	s_waitcnt lgkmcnt(7)
	global_store_dwordx4 v169, v[64:67], s[20:21]
	v_add_u32_e32 v169, 0x8000, v169
	s_waitcnt lgkmcnt(6)
	global_store_dwordx4 v169, v[68:71], s[20:21]
	v_add_u32_e32 v169, 0x8000, v169
	s_waitcnt lgkmcnt(5)
	global_store_dwordx4 v169, v[72:75], s[20:21]
	v_add_u32_e32 v169, 0x8000, v169
	s_waitcnt lgkmcnt(4)
	global_store_dwordx4 v169, v[76:79], s[20:21]
	v_add_u32_e32 v169, 0x8000, v169
	s_waitcnt lgkmcnt(3)
	global_store_dwordx4 v169, v[80:83], s[20:21]
	v_add_u32_e32 v169, 0x8000, v169
	s_waitcnt lgkmcnt(2)
	global_store_dwordx4 v169, v[84:87], s[20:21]
	v_add_u32_e32 v169, 0x8000, v169
	s_waitcnt lgkmcnt(1)
	global_store_dwordx4 v169, v[88:91], s[20:21]
	v_add_u32_e32 v169, 0x8000, v169
	s_waitcnt lgkmcnt(0)
	global_store_dwordx4 v169, v[92:95], s[20:21]
	v_add_u32_e32 v169, 0x8000, v169
	s_branch .LBB0_261

; DEV u16 f2bf(float f) { return (u16)(pack2(f, f) & 0xffffu); }
; template <class F>
; DEV void acc_foreach(Acc& acc, int m0, int n0, F f) {
;   asm volatile("s_nop 7\n\ts_nop 7\n\ts_nop 3" ::: "memory");
;   const int tid = tidx_full();
;   const int wave = tid >> 6, lane = tid & 63;
;   const int wm = (wave >> 2) * 128, wn = (wave & 3) * 64;
;   const int lr = lane & 31, lh = lane >> 5;
; #pragma unroll
;   for (int i = 0; i < 4; ++i)
; #pragma unroll
;     for (int j = 0; j < 2; ++j)
; #pragma unroll
;       for (int r = 0; r < 16; ++r) {
;         const int m = m0 + wm + 32 * i + (r & 3) + 8 * (r >> 2) + 4 * lh;
;         const int n = n0 + wn + 32 * j + lr;
;         float v = acc[i][j][r];
;         f(m, n, v);
;         acc[i][j][r] = v;
;       }
; DEV void phase_p1(const Params& p, int g, char* smem) {
;     ...
;       const int b = n0 / L, tb = n0 - b * L;
;       u16* dst = UHY + (size_t)b * 1536 * L + tb - n0;
;       acc_foreach(acc, m0, n0, [&](int m, int n, float& v) { dst[(size_t)m * L + n] = f2bf(v); });
.Lp1b_d4:
.Lp1b_nomore:
	s_lshr_b32 s3, s2, s24
	s_lshl_b32 s4, s3, s24
	s_sub_u32 s4, s2, s4
	s_mul_i32 s5, s3, 0x600
	s_add_u32 s5, s5, s11
	s_add_u32 s12, s24, 1
	s_lshl_b32 s13, 8, s12
	s_nop 7
	s_nop 7
	s_nop 3
	v_and_b32_e32 v160, 63, v202
	v_lshrrev_b32_e32 v161, 6, v202
	v_and_b32_e32 v164, 3, v161
	v_lshlrev_b32_e32 v164, 13, v164
	v_add_u32_e32 v164, 0x8000, v164
	v_lshrrev_b32_e32 v160, 2, v161
	v_lshl_add_u32 v164, v160, 16, v164
	v_and_b32_e32 v160, 63, v202
	v_and_b32_e32 v166, 15, v160
	v_lshrrev_b32_e32 v167, 4, v160
	v_lshl_add_u32 v168, v166, 7, v164
	v_and_b32_e32 v169, 1, v167
	v_lshl_add_u32 v168, v169, 3, v168
	v_lshrrev_b32_e32 v167, 1, v167
	v_and_b32_e32 v166, 7, v166
	v_xor_b32_e32 v166, v166, v167
	v_lshlrev_b32_e32 v166, 4, v166
	v_add_u32_e32 v170, v168, v166
	v_xor_b32_e32 v167, 0x20, v166
	v_add_u32_e32 v171, v168, v167
	v_xor_b32_e32 v167, 0x40, v166
	v_add_u32_e32 v172, v168, v167
	v_xor_b32_e32 v167, 0x60, v166
	v_add_u32_e32 v173, v168, v167
	v_and_b32_e32 v166, 31, v160
	v_lshrrev_b32_e32 v167, 5, v160
	v_lshlrev_b32_e32 v168, 7, v166
	v_lshl_add_u32 v168, v167, 3, v168
	v_add_u32_e32 v168, v164, v168
	v_and_b32_e32 v166, 7, v166
	v_lshlrev_b32_e32 v166, 4, v166
	v_lshrrev_b32_e32 v166, 3, v160
	v_and_b32_e32 v167, 7, v160
	v_lshrrev_b32_e32 v169, 2, v161
	v_lshl_add_u32 v169, v169, 7, v166
	v_add_u32_e32 v169, s5, v169
	v_lshlrev_b32_e32 v169, s12, v169
	v_and_b32_e32 v168, 3, v161
	v_lshlrev_b32_e32 v168, 3, v168
	v_add_u32_e32 v168, v168, v167
	v_lshl_add_u32 v169, v168, 4, v169
	s_lshl_b32 s100, s4, 1
	v_add_u32_e32 v169, s100, v169
	v_xor_b32_e32 v167, v166, v167
	v_lshlrev_b32_e32 v167, 4, v167
	v_lshl_add_u32 v168, v166, 7, v167
	v_add_u32_e32 v168, v164, v168
	v_cvt_pk_bf16_f32 v0, v0, v1
	v_cvt_pk_bf16_f32 v1, v2, v3
	ds_write_b64 v170, v[0:1]
	v_cvt_pk_bf16_f32 v4, v4, v5
	v_cvt_pk_bf16_f32 v5, v6, v7
	ds_write_b64 v171, v[4:5]
	v_cvt_pk_bf16_f32 v8, v8, v9
	v_cvt_pk_bf16_f32 v9, v10, v11
	ds_write_b64 v172, v[8:9]
	v_cvt_pk_bf16_f32 v12, v12, v13
	v_cvt_pk_bf16_f32 v13, v14, v15
	ds_write_b64 v173, v[12:13]
	v_cvt_pk_bf16_f32 v16, v16, v17
	v_cvt_pk_bf16_f32 v17, v18, v19
	ds_write_b64 v170, v[16:17] offset:2048
	v_cvt_pk_bf16_f32 v20, v20, v21
	v_cvt_pk_bf16_f32 v21, v22, v23
	ds_write_b64 v171, v[20:21] offset:2048
	v_cvt_pk_bf16_f32 v24, v24, v25
	v_cvt_pk_bf16_f32 v25, v26, v27
	ds_write_b64 v172, v[24:25] offset:2048
	v_cvt_pk_bf16_f32 v28, v28, v29
	v_cvt_pk_bf16_f32 v29, v30, v31
	ds_write_b64 v173, v[28:29] offset:2048
	v_cvt_pk_bf16_f32 v32, v32, v33
	v_cvt_pk_bf16_f32 v33, v34, v35
	ds_write_b64 v170, v[32:33] offset:4096
	v_cvt_pk_bf16_f32 v36, v36, v37
	v_cvt_pk_bf16_f32 v37, v38, v39
	ds_write_b64 v171, v[36:37] offset:4096
	v_cvt_pk_bf16_f32 v40, v40, v41
	v_cvt_pk_bf16_f32 v41, v42, v43
	ds_write_b64 v172, v[40:41] offset:4096
	v_cvt_pk_bf16_f32 v44, v44, v45
	v_cvt_pk_bf16_f32 v45, v46, v47
	ds_write_b64 v173, v[44:45] offset:4096
	v_cvt_pk_bf16_f32 v48, v48, v49
	v_cvt_pk_bf16_f32 v49, v50, v51
	ds_write_b64 v170, v[48:49] offset:6144
	v_cvt_pk_bf16_f32 v52, v52, v53
	v_cvt_pk_bf16_f32 v53, v54, v55
	ds_write_b64 v171, v[52:53] offset:6144
	v_cvt_pk_bf16_f32 v56, v56, v57
	v_cvt_pk_bf16_f32 v57, v58, v59
	ds_write_b64 v172, v[56:57] offset:6144
	v_cvt_pk_bf16_f32 v60, v60, v61
	v_cvt_pk_bf16_f32 v61, v62, v63
	ds_write_b64 v173, v[60:61] offset:6144
	s_waitcnt lgkmcnt(0)
	ds_read_b128 v[32:35], v168
	ds_read_b128 v[36:39], v168 offset:1024
	ds_read_b128 v[40:43], v168 offset:2048
	ds_read_b128 v[44:47], v168 offset:3072
	ds_read_b128 v[48:51], v168 offset:4096
	ds_read_b128 v[52:55], v168 offset:5120
	ds_read_b128 v[56:59], v168 offset:6144
	ds_read_b128 v[60:63], v168 offset:7168
	s_waitcnt lgkmcnt(7)
; DEV u16 f2bf(float f) { return (u16)(pack2(f, f) & 0xffffu); }
; template <class F>
; DEV void acc_foreach(Acc& acc, int m0, int n0, F f) {
;   asm volatile("s_nop 7\n\ts_nop 7\n\ts_nop 3" ::: "memory");
;   const int tid = tidx_full();
;   const int wave = tid >> 6, lane = tid & 63;
;   const int wm = (wave >> 2) * 128, wn = (wave & 3) * 64;
;   const int lr = lane & 31, lh = lane >> 5;
; #pragma unroll
;   for (int i = 0; i < 4; ++i)
; #pragma unroll
;     for (int j = 0; j < 2; ++j)
; #pragma unroll
;       for (int r = 0; r < 16; ++r) {
;         const int m = m0 + wm + 32 * i + (r & 3) + 8 * (r >> 2) + 4 * lh;
;         const int n = n0 + wn + 32 * j + lr;
;         float v = acc[i][j][r];
;         f(m, n, v);
;         acc[i][j][r] = v;
;       }
; DEV void phase_p1(const Params& p, int g, char* smem) {
;     ...
;       const int b = n0 / L, tb = n0 - b * L;
;       u16* dst = UHY + (size_t)b * 1536 * L + tb - n0;
;       acc_foreach(acc, m0, n0, [&](int m, int n, float& v) { dst[(size_t)m * L + n] = f2bf(v); });
	global_store_dwordx4 v169, v[32:35], s[74:75]
	v_add_u32_e32 v169, s13, v169
	s_waitcnt lgkmcnt(6)
	global_store_dwordx4 v169, v[36:39], s[74:75]
	v_add_u32_e32 v169, s13, v169
	s_waitcnt lgkmcnt(5)
	global_store_dwordx4 v169, v[40:43], s[74:75]
	v_add_u32_e32 v169, s13, v169
	s_waitcnt lgkmcnt(4)
	global_store_dwordx4 v169, v[44:47], s[74:75]
	v_add_u32_e32 v169, s13, v169
	s_waitcnt lgkmcnt(3)
	global_store_dwordx4 v169, v[48:51], s[74:75]
	v_add_u32_e32 v169, s13, v169
	s_waitcnt lgkmcnt(2)
	global_store_dwordx4 v169, v[52:55], s[74:75]
	v_add_u32_e32 v169, s13, v169
	s_waitcnt lgkmcnt(1)
	global_store_dwordx4 v169, v[56:59], s[74:75]
	v_add_u32_e32 v169, s13, v169
	s_waitcnt lgkmcnt(0)
	global_store_dwordx4 v169, v[60:63], s[74:75]
	v_add_u32_e32 v169, s13, v169
	v_cvt_pk_bf16_f32 v64, v64, v65
	v_cvt_pk_bf16_f32 v65, v66, v67
	ds_write_b64 v170, v[64:65]
	v_cvt_pk_bf16_f32 v68, v68, v69
	v_cvt_pk_bf16_f32 v69, v70, v71
	ds_write_b64 v171, v[68:69]
	v_cvt_pk_bf16_f32 v72, v72, v73
	v_cvt_pk_bf16_f32 v73, v74, v75
	ds_write_b64 v172, v[72:73]
	v_cvt_pk_bf16_f32 v76, v76, v77
	v_cvt_pk_bf16_f32 v77, v78, v79
	ds_write_b64 v173, v[76:77]
	v_cvt_pk_bf16_f32 v80, v80, v81
	v_cvt_pk_bf16_f32 v81, v82, v83
	ds_write_b64 v170, v[80:81] offset:2048
	v_cvt_pk_bf16_f32 v84, v84, v85
	v_cvt_pk_bf16_f32 v85, v86, v87
	ds_write_b64 v171, v[84:85] offset:2048
	v_cvt_pk_bf16_f32 v88, v88, v89
	v_cvt_pk_bf16_f32 v89, v90, v91
	ds_write_b64 v172, v[88:89] offset:2048
	v_cvt_pk_bf16_f32 v92, v92, v93
	v_cvt_pk_bf16_f32 v93, v94, v95
	ds_write_b64 v173, v[92:93] offset:2048
	v_cvt_pk_bf16_f32 v96, v96, v97
	v_cvt_pk_bf16_f32 v97, v98, v99
	ds_write_b64 v170, v[96:97] offset:4096
	v_cvt_pk_bf16_f32 v100, v100, v101
	v_cvt_pk_bf16_f32 v101, v102, v103
	ds_write_b64 v171, v[100:101] offset:4096
	v_cvt_pk_bf16_f32 v104, v104, v105
	v_cvt_pk_bf16_f32 v105, v106, v107
	ds_write_b64 v172, v[104:105] offset:4096
	v_cvt_pk_bf16_f32 v108, v108, v109
	v_cvt_pk_bf16_f32 v109, v110, v111
	ds_write_b64 v173, v[108:109] offset:4096
	v_cvt_pk_bf16_f32 v112, v112, v113
	v_cvt_pk_bf16_f32 v113, v114, v115
	ds_write_b64 v170, v[112:113] offset:6144
	v_cvt_pk_bf16_f32 v116, v116, v117
	v_cvt_pk_bf16_f32 v117, v118, v119
	ds_write_b64 v171, v[116:117] offset:6144
	v_cvt_pk_bf16_f32 v120, v120, v121
	v_cvt_pk_bf16_f32 v121, v122, v123
	ds_write_b64 v172, v[120:121] offset:6144
	v_cvt_pk_bf16_f32 v124, v124, v125
	v_cvt_pk_bf16_f32 v125, v126, v127
	ds_write_b64 v173, v[124:125] offset:6144
	s_waitcnt lgkmcnt(0)
	ds_read_b128 v[64:67], v168
	ds_read_b128 v[68:71], v168 offset:1024
	ds_read_b128 v[72:75], v168 offset:2048
	ds_read_b128 v[76:79], v168 offset:3072
	ds_read_b128 v[80:83], v168 offset:4096
	ds_read_b128 v[84:87], v168 offset:5120
	ds_read_b128 v[88:91], v168 offset:6144
	ds_read_b128 v[92:95], v168 offset:7168
	s_waitcnt lgkmcnt(7)
	global_store_dwordx4 v169, v[64:67], s[74:75]
	v_add_u32_e32 v169, s13, v169
	s_waitcnt lgkmcnt(6)
	global_store_dwordx4 v169, v[68:71], s[74:75]
	v_add_u32_e32 v169, s13, v169
	s_waitcnt lgkmcnt(5)
	global_store_dwordx4 v169, v[72:75], s[74:75]
	v_add_u32_e32 v169, s13, v169
	s_waitcnt lgkmcnt(4)
	global_store_dwordx4 v169, v[76:79], s[74:75]
	v_add_u32_e32 v169, s13, v169
	s_waitcnt lgkmcnt(3)
	global_store_dwordx4 v169, v[80:83], s[74:75]
	v_add_u32_e32 v169, s13, v169
	s_waitcnt lgkmcnt(2)
	global_store_dwordx4 v169, v[84:87], s[74:75]
	v_add_u32_e32 v169, s13, v169
	s_waitcnt lgkmcnt(1)
	global_store_dwordx4 v169, v[88:91], s[74:75]
	v_add_u32_e32 v169, s13, v169
	s_waitcnt lgkmcnt(0)
	global_store_dwordx4 v169, v[92:95], s[74:75]
	v_add_u32_e32 v169, s13, v169
	s_mov_b64 s[4:5], 0
	s_branch .LBB0_544

; DEV u16 f2bf(float f) { return (u16)(pack2(f, f) & 0xffffu); }
; template <class F>
; DEV void acc_foreach(Acc& acc, int m0, int n0, F f) {
;   asm volatile("s_nop 7\n\ts_nop 7\n\ts_nop 3" ::: "memory");
;   const int tid = tidx_full();
;   const int wave = tid >> 6, lane = tid & 63;
;   const int wm = (wave >> 2) * 128, wn = (wave & 3) * 64;
;   const int lr = lane & 31, lh = lane >> 5;
; #pragma unroll
;   for (int i = 0; i < 4; ++i)
; #pragma unroll
;     for (int j = 0; j < 2; ++j)
; #pragma unroll
;       for (int r = 0; r < 16; ++r) {
;         const int m = m0 + wm + 32 * i + (r & 3) + 8 * (r >> 2) + 4 * lh;
;         const int n = n0 + wn + 32 * j + lr;
;         float v = acc[i][j][r];
;         f(m, n, v);
;         acc[i][j][r] = v;
;       }
; DEV void phase_ff1(const Params& p, int g, char* smem) {
;     ...
;     acc_foreach(acc, m0, n0, [&](int m, int n, float& v) {
;       const float r = fmaxf(v, 0.f);
;       AB[(size_t)m * 4096 + n] = f2bf(r * r);
;     });
.Lff1_d4:
.Lff1_nomore:
	s_nop 7
	s_nop 7
	s_nop 3
	v_and_b32_e32 v160, 63, v202
	v_lshrrev_b32_e32 v161, 6, v202
	v_and_b32_e32 v164, 3, v161
	v_lshlrev_b32_e32 v164, 13, v164
	v_add_u32_e32 v164, 0x8000, v164
	v_lshrrev_b32_e32 v160, 2, v161
	v_lshl_add_u32 v164, v160, 16, v164
	v_and_b32_e32 v160, 63, v202
	v_and_b32_e32 v166, 15, v160
	v_lshrrev_b32_e32 v167, 4, v160
	v_lshl_add_u32 v168, v166, 7, v164
	v_and_b32_e32 v169, 1, v167
	v_lshl_add_u32 v168, v169, 3, v168
	v_lshrrev_b32_e32 v167, 1, v167
	v_and_b32_e32 v166, 7, v166
	v_xor_b32_e32 v166, v166, v167
	v_lshlrev_b32_e32 v166, 4, v166
	v_add_u32_e32 v170, v168, v166
	v_xor_b32_e32 v167, 0x20, v166
	v_add_u32_e32 v171, v168, v167
	v_xor_b32_e32 v167, 0x40, v166
	v_add_u32_e32 v172, v168, v167
	v_xor_b32_e32 v167, 0x60, v166
	v_add_u32_e32 v173, v168, v167
	v_and_b32_e32 v166, 31, v160
	v_lshrrev_b32_e32 v167, 5, v160
	v_lshlrev_b32_e32 v168, 7, v166
	v_lshl_add_u32 v168, v167, 3, v168
	v_add_u32_e32 v168, v164, v168
	v_and_b32_e32 v166, 7, v166
	v_lshlrev_b32_e32 v166, 4, v166
	v_lshrrev_b32_e32 v166, 3, v160
	v_and_b32_e32 v167, 7, v160
	v_lshrrev_b32_e32 v169, 2, v161
	v_lshl_add_u32 v169, v169, 7, v166
	v_add_u32_e32 v169, s5, v169
	v_mul_u32_u24_e32 v169, 0x2000, v169
	v_and_b32_e32 v168, 3, v161
	v_lshlrev_b32_e32 v168, 3, v168
	v_add_u32_e32 v168, v168, v167
	v_lshl_add_u32 v169, v168, 4, v169
	s_lshl_b32 s100, s4, 1
	v_add_u32_e32 v169, s100, v169
	v_xor_b32_e32 v167, v166, v167
	v_lshlrev_b32_e32 v167, 4, v167
	v_lshl_add_u32 v168, v166, 7, v167
	v_add_u32_e32 v168, v164, v168
	v_max_f32_e32 v0, 0, v0
	v_max_f32_e32 v1, 0, v1
	v_max_f32_e32 v2, 0, v2
	v_max_f32_e32 v3, 0, v3
	v_mul_f32_e32 v0, v0, v0
	v_mul_f32_e32 v1, v1, v1
	v_mul_f32_e32 v2, v2, v2
	v_mul_f32_e32 v3, v3, v3
	v_cvt_pk_bf16_f32 v0, v0, v1
	v_cvt_pk_bf16_f32 v1, v2, v3
	ds_write_b64 v170, v[0:1]
	v_max_f32_e32 v4, 0, v4
	v_max_f32_e32 v5, 0, v5
	v_max_f32_e32 v6, 0, v6
	v_max_f32_e32 v7, 0, v7
	v_mul_f32_e32 v4, v4, v4
	v_mul_f32_e32 v5, v5, v5
	v_mul_f32_e32 v6, v6, v6
	v_mul_f32_e32 v7, v7, v7
	v_cvt_pk_bf16_f32 v4, v4, v5
	v_cvt_pk_bf16_f32 v5, v6, v7
	ds_write_b64 v171, v[4:5]
	v_max_f32_e32 v8, 0, v8
	v_max_f32_e32 v9, 0, v9
	v_max_f32_e32 v10, 0, v10
	v_max_f32_e32 v11, 0, v11
	v_mul_f32_e32 v8, v8, v8
	v_mul_f32_e32 v9, v9, v9
	v_mul_f32_e32 v10, v10, v10
	v_mul_f32_e32 v11, v11, v11
	v_cvt_pk_bf16_f32 v8, v8, v9
	v_cvt_pk_bf16_f32 v9, v10, v11
	ds_write_b64 v172, v[8:9]
	v_max_f32_e32 v12, 0, v12
	v_max_f32_e32 v13, 0, v13
	v_max_f32_e32 v14, 0, v14
	v_max_f32_e32 v15, 0, v15
	v_mul_f32_e32 v12, v12, v12
	v_mul_f32_e32 v13, v13, v13
	v_mul_f32_e32 v14, v14, v14
	v_mul_f32_e32 v15, v15, v15
	v_cvt_pk_bf16_f32 v12, v12, v13
	v_cvt_pk_bf16_f32 v13, v14, v15
	ds_write_b64 v173, v[12:13]
	v_max_f32_e32 v16, 0, v16
	v_max_f32_e32 v17, 0, v17
	v_max_f32_e32 v18, 0, v18
	v_max_f32_e32 v19, 0, v19
	v_mul_f32_e32 v16, v16, v16
	v_mul_f32_e32 v17, v17, v17
	v_mul_f32_e32 v18, v18, v18
	v_mul_f32_e32 v19, v19, v19
	v_cvt_pk_bf16_f32 v16, v16, v17
	v_cvt_pk_bf16_f32 v17, v18, v19
	ds_write_b64 v170, v[16:17] offset:2048
	v_max_f32_e32 v20, 0, v20
	v_max_f32_e32 v21, 0, v21
	v_max_f32_e32 v22, 0, v22
	v_max_f32_e32 v23, 0, v23
	v_mul_f32_e32 v20, v20, v20
	v_mul_f32_e32 v21, v21, v21
	v_mul_f32_e32 v22, v22, v22
	v_mul_f32_e32 v23, v23, v23
	v_cvt_pk_bf16_f32 v20, v20, v21
	v_cvt_pk_bf16_f32 v21, v22, v23
	ds_write_b64 v171, v[20:21] offset:2048
	v_max_f32_e32 v24, 0, v24
	v_max_f32_e32 v25, 0, v25
	v_max_f32_e32 v26, 0, v26
	v_max_f32_e32 v27, 0, v27
	v_mul_f32_e32 v24, v24, v24
	v_mul_f32_e32 v25, v25, v25
	v_mul_f32_e32 v26, v26, v26
	v_mul_f32_e32 v27, v27, v27
	v_cvt_pk_bf16_f32 v24, v24, v25
	v_cvt_pk_bf16_f32 v25, v26, v27
	ds_write_b64 v172, v[24:25] offset:2048
	v_max_f32_e32 v28, 0, v28
	v_max_f32_e32 v29, 0, v29
	v_max_f32_e32 v30, 0, v30
	v_max_f32_e32 v31, 0, v31
	v_mul_f32_e32 v28, v28, v28
	v_mul_f32_e32 v29, v29, v29
	v_mul_f32_e32 v30, v30, v30
	v_mul_f32_e32 v31, v31, v31
	v_cvt_pk_bf16_f32 v28, v28, v29
	v_cvt_pk_bf16_f32 v29, v30, v31
	ds_write_b64 v173, v[28:29] offset:2048
	v_max_f32_e32 v32, 0, v32
	v_max_f32_e32 v33, 0, v33
	v_max_f32_e32 v34, 0, v34
	v_max_f32_e32 v35, 0, v35
	v_mul_f32_e32 v32, v32, v32
	v_mul_f32_e32 v33, v33, v33
	v_mul_f32_e32 v34, v34, v34
	v_mul_f32_e32 v35, v35, v35
	v_cvt_pk_bf16_f32 v32, v32, v33
	v_cvt_pk_bf16_f32 v33, v34, v35
	ds_write_b64 v170, v[32:33] offset:4096
	v_max_f32_e32 v36, 0, v36
	v_max_f32_e32 v37, 0, v37
	v_max_f32_e32 v38, 0, v38
	v_max_f32_e32 v39, 0, v39
	v_mul_f32_e32 v36, v36, v36
	v_mul_f32_e32 v37, v37, v37
	v_mul_f32_e32 v38, v38, v38
	v_mul_f32_e32 v39, v39, v39
	v_cvt_pk_bf16_f32 v36, v36, v37
	v_cvt_pk_bf16_f32 v37, v38, v39
	ds_write_b64 v171, v[36:37] offset:4096
	v_max_f32_e32 v40, 0, v40
	v_max_f32_e32 v41, 0, v41
	v_max_f32_e32 v42, 0, v42
	v_max_f32_e32 v43, 0, v43
	v_mul_f32_e32 v40, v40, v40
	v_mul_f32_e32 v41, v41, v41
	v_mul_f32_e32 v42, v42, v42
	v_mul_f32_e32 v43, v43, v43
	v_cvt_pk_bf16_f32 v40, v40, v41
	v_cvt_pk_bf16_f32 v41, v42, v43
	ds_write_b64 v172, v[40:41] offset:4096
	v_max_f32_e32 v44, 0, v44
	v_max_f32_e32 v45, 0, v45
	v_max_f32_e32 v46, 0, v46
	v_max_f32_e32 v47, 0, v47
	v_mul_f32_e32 v44, v44, v44
	v_mul_f32_e32 v45, v45, v45
	v_mul_f32_e32 v46, v46, v46
	v_mul_f32_e32 v47, v47, v47
	v_cvt_pk_bf16_f32 v44, v44, v45
	v_cvt_pk_bf16_f32 v45, v46, v47
	ds_write_b64 v173, v[44:45] offset:4096
	v_max_f32_e32 v48, 0, v48
	v_max_f32_e32 v49, 0, v49
	v_max_f32_e32 v50, 0, v50
	v_max_f32_e32 v51, 0, v51
	v_mul_f32_e32 v48, v48, v48
	v_mul_f32_e32 v49, v49, v49
	v_mul_f32_e32 v50, v50, v50
	v_mul_f32_e32 v51, v51, v51
	v_cvt_pk_bf16_f32 v48, v48, v49
	v_cvt_pk_bf16_f32 v49, v50, v51
	ds_write_b64 v170, v[48:49] offset:6144
	v_max_f32_e32 v52, 0, v52
	v_max_f32_e32 v53, 0, v53
	v_max_f32_e32 v54, 0, v54
	v_max_f32_e32 v55, 0, v55
	v_mul_f32_e32 v52, v52, v52
	v_mul_f32_e32 v53, v53, v53
	v_mul_f32_e32 v54, v54, v54
	v_mul_f32_e32 v55, v55, v55
	v_cvt_pk_bf16_f32 v52, v52, v53
	v_cvt_pk_bf16_f32 v53, v54, v55
	ds_write_b64 v171, v[52:53] offset:6144
	v_max_f32_e32 v56, 0, v56
	v_max_f32_e32 v57, 0, v57
	v_max_f32_e32 v58, 0, v58
	v_max_f32_e32 v59, 0, v59
	v_mul_f32_e32 v56, v56, v56
	v_mul_f32_e32 v57, v57, v57
	v_mul_f32_e32 v58, v58, v58
	v_mul_f32_e32 v59, v59, v59
	v_cvt_pk_bf16_f32 v56, v56, v57
	v_cvt_pk_bf16_f32 v57, v58, v59
	ds_write_b64 v172, v[56:57] offset:6144
	v_max_f32_e32 v60, 0, v60
	v_max_f32_e32 v61, 0, v61
	v_max_f32_e32 v62, 0, v62
	v_max_f32_e32 v63, 0, v63
	v_mul_f32_e32 v60, v60, v60
	v_mul_f32_e32 v61, v61, v61
	v_mul_f32_e32 v62, v62, v62
	v_mul_f32_e32 v63, v63, v63
	v_cvt_pk_bf16_f32 v60, v60, v61
	v_cvt_pk_bf16_f32 v61, v62, v63
	ds_write_b64 v173, v[60:61] offset:6144
	s_waitcnt lgkmcnt(0)
; DEV u16 f2bf(float f) { return (u16)(pack2(f, f) & 0xffffu); }
; template <class F>
; DEV void acc_foreach(Acc& acc, int m0, int n0, F f) {
;   asm volatile("s_nop 7\n\ts_nop 7\n\ts_nop 3" ::: "memory");
;   const int tid = tidx_full();
;   const int wave = tid >> 6, lane = tid & 63;
;   const int wm = (wave >> 2) * 128, wn = (wave & 3) * 64;
;   const int lr = lane & 31, lh = lane >> 5;
; #pragma unroll
;   for (int i = 0; i < 4; ++i)
; #pragma unroll
;     for (int j = 0; j < 2; ++j)
; #pragma unroll
;       for (int r = 0; r < 16; ++r) {
;         const int m = m0 + wm + 32 * i + (r & 3) + 8 * (r >> 2) + 4 * lh;
;         const int n = n0 + wn + 32 * j + lr;
;         float v = acc[i][j][r];
;         f(m, n, v);
;         acc[i][j][r] = v;
;       }
; DEV void phase_ff1(const Params& p, int g, char* smem) {
;     ...
;     acc_foreach(acc, m0, n0, [&](int m, int n, float& v) {
;       const float r = fmaxf(v, 0.f);
;       AB[(size_t)m * 4096 + n] = f2bf(r * r);
;     });
	ds_read_b128 v[32:35], v168
	ds_read_b128 v[36:39], v168 offset:1024
	ds_read_b128 v[40:43], v168 offset:2048
	ds_read_b128 v[44:47], v168 offset:3072
	ds_read_b128 v[48:51], v168 offset:4096
	ds_read_b128 v[52:55], v168 offset:5120
	ds_read_b128 v[56:59], v168 offset:6144
	ds_read_b128 v[60:63], v168 offset:7168
	s_waitcnt lgkmcnt(7)
	global_store_dwordx4 v169, v[32:35], s[74:75]
	v_add_u32_e32 v169, 0x10000, v169
	s_waitcnt lgkmcnt(6)
	global_store_dwordx4 v169, v[36:39], s[74:75]
	v_add_u32_e32 v169, 0x10000, v169
	s_waitcnt lgkmcnt(5)
	global_store_dwordx4 v169, v[40:43], s[74:75]
	v_add_u32_e32 v169, 0x10000, v169
	s_waitcnt lgkmcnt(4)
	global_store_dwordx4 v169, v[44:47], s[74:75]
	v_add_u32_e32 v169, 0x10000, v169
	s_waitcnt lgkmcnt(3)
	global_store_dwordx4 v169, v[48:51], s[74:75]
	v_add_u32_e32 v169, 0x10000, v169
	s_waitcnt lgkmcnt(2)
	global_store_dwordx4 v169, v[52:55], s[74:75]
	v_add_u32_e32 v169, 0x10000, v169
	s_waitcnt lgkmcnt(1)
	global_store_dwordx4 v169, v[56:59], s[74:75]
	v_add_u32_e32 v169, 0x10000, v169
	s_waitcnt lgkmcnt(0)
	global_store_dwordx4 v169, v[60:63], s[74:75]
	v_add_u32_e32 v169, 0x10000, v169
	v_max_f32_e32 v64, 0, v64
	v_max_f32_e32 v65, 0, v65
	v_max_f32_e32 v66, 0, v66
	v_max_f32_e32 v67, 0, v67
	v_mul_f32_e32 v64, v64, v64
	v_mul_f32_e32 v65, v65, v65
	v_mul_f32_e32 v66, v66, v66
	v_mul_f32_e32 v67, v67, v67
	v_cvt_pk_bf16_f32 v64, v64, v65
	v_cvt_pk_bf16_f32 v65, v66, v67
	ds_write_b64 v170, v[64:65]
	v_max_f32_e32 v68, 0, v68
	v_max_f32_e32 v69, 0, v69
	v_max_f32_e32 v70, 0, v70
	v_max_f32_e32 v71, 0, v71
	v_mul_f32_e32 v68, v68, v68
	v_mul_f32_e32 v69, v69, v69
	v_mul_f32_e32 v70, v70, v70
	v_mul_f32_e32 v71, v71, v71
	v_cvt_pk_bf16_f32 v68, v68, v69
	v_cvt_pk_bf16_f32 v69, v70, v71
	ds_write_b64 v171, v[68:69]
	v_max_f32_e32 v72, 0, v72
	v_max_f32_e32 v73, 0, v73
	v_max_f32_e32 v74, 0, v74
	v_max_f32_e32 v75, 0, v75
	v_mul_f32_e32 v72, v72, v72
	v_mul_f32_e32 v73, v73, v73
	v_mul_f32_e32 v74, v74, v74
	v_mul_f32_e32 v75, v75, v75
	v_cvt_pk_bf16_f32 v72, v72, v73
	v_cvt_pk_bf16_f32 v73, v74, v75
	ds_write_b64 v172, v[72:73]
	v_max_f32_e32 v76, 0, v76
	v_max_f32_e32 v77, 0, v77
	v_max_f32_e32 v78, 0, v78
	v_max_f32_e32 v79, 0, v79
	v_mul_f32_e32 v76, v76, v76
	v_mul_f32_e32 v77, v77, v77
	v_mul_f32_e32 v78, v78, v78
	v_mul_f32_e32 v79, v79, v79
	v_cvt_pk_bf16_f32 v76, v76, v77
	v_cvt_pk_bf16_f32 v77, v78, v79
	ds_write_b64 v173, v[76:77]
	v_max_f32_e32 v80, 0, v80
	v_max_f32_e32 v81, 0, v81
	v_max_f32_e32 v82, 0, v82
	v_max_f32_e32 v83, 0, v83
	v_mul_f32_e32 v80, v80, v80
	v_mul_f32_e32 v81, v81, v81
	v_mul_f32_e32 v82, v82, v82
	v_mul_f32_e32 v83, v83, v83
	v_cvt_pk_bf16_f32 v80, v80, v81
	v_cvt_pk_bf16_f32 v81, v82, v83
	ds_write_b64 v170, v[80:81] offset:2048
	v_max_f32_e32 v84, 0, v84
	v_max_f32_e32 v85, 0, v85
	v_max_f32_e32 v86, 0, v86
	v_max_f32_e32 v87, 0, v87
	v_mul_f32_e32 v84, v84, v84
	v_mul_f32_e32 v85, v85, v85
	v_mul_f32_e32 v86, v86, v86
	v_mul_f32_e32 v87, v87, v87
	v_cvt_pk_bf16_f32 v84, v84, v85
	v_cvt_pk_bf16_f32 v85, v86, v87
	ds_write_b64 v171, v[84:85] offset:2048
	v_max_f32_e32 v88, 0, v88
	v_max_f32_e32 v89, 0, v89
	v_max_f32_e32 v90, 0, v90
	v_max_f32_e32 v91, 0, v91
	v_mul_f32_e32 v88, v88, v88
	v_mul_f32_e32 v89, v89, v89
	v_mul_f32_e32 v90, v90, v90
	v_mul_f32_e32 v91, v91, v91
	v_cvt_pk_bf16_f32 v88, v88, v89
	v_cvt_pk_bf16_f32 v89, v90, v91
	ds_write_b64 v172, v[88:89] offset:2048
	v_max_f32_e32 v92, 0, v92
	v_max_f32_e32 v93, 0, v93
	v_max_f32_e32 v94, 0, v94
	v_max_f32_e32 v95, 0, v95
	v_mul_f32_e32 v92, v92, v92
	v_mul_f32_e32 v93, v93, v93
	v_mul_f32_e32 v94, v94, v94
	v_mul_f32_e32 v95, v95, v95
	v_cvt_pk_bf16_f32 v92, v92, v93
	v_cvt_pk_bf16_f32 v93, v94, v95
	ds_write_b64 v173, v[92:93] offset:2048
	v_max_f32_e32 v96, 0, v96
	v_max_f32_e32 v97, 0, v97
	v_max_f32_e32 v98, 0, v98
	v_max_f32_e32 v99, 0, v99
	v_mul_f32_e32 v96, v96, v96
	v_mul_f32_e32 v97, v97, v97
	v_mul_f32_e32 v98, v98, v98
	v_mul_f32_e32 v99, v99, v99
	v_cvt_pk_bf16_f32 v96, v96, v97
	v_cvt_pk_bf16_f32 v97, v98, v99
	ds_write_b64 v170, v[96:97] offset:4096
	v_max_f32_e32 v100, 0, v100
	v_max_f32_e32 v101, 0, v101
	v_max_f32_e32 v102, 0, v102
	v_max_f32_e32 v103, 0, v103
	v_mul_f32_e32 v100, v100, v100
	v_mul_f32_e32 v101, v101, v101
	v_mul_f32_e32 v102, v102, v102
	v_mul_f32_e32 v103, v103, v103
	v_cvt_pk_bf16_f32 v100, v100, v101
	v_cvt_pk_bf16_f32 v101, v102, v103
	ds_write_b64 v171, v[100:101] offset:4096
	v_max_f32_e32 v104, 0, v104
	v_max_f32_e32 v105, 0, v105
	v_max_f32_e32 v106, 0, v106
	v_max_f32_e32 v107, 0, v107
	v_mul_f32_e32 v104, v104, v104
	v_mul_f32_e32 v105, v105, v105
	v_mul_f32_e32 v106, v106, v106
	v_mul_f32_e32 v107, v107, v107
	v_cvt_pk_bf16_f32 v104, v104, v105
	v_cvt_pk_bf16_f32 v105, v106, v107
	ds_write_b64 v172, v[104:105] offset:4096
	v_max_f32_e32 v108, 0, v108
	v_max_f32_e32 v109, 0, v109
	v_max_f32_e32 v110, 0, v110
	v_max_f32_e32 v111, 0, v111
	v_mul_f32_e32 v108, v108, v108
	v_mul_f32_e32 v109, v109, v109
	v_mul_f32_e32 v110, v110, v110
	v_mul_f32_e32 v111, v111, v111
	v_cvt_pk_bf16_f32 v108, v108, v109
	v_cvt_pk_bf16_f32 v109, v110, v111
	ds_write_b64 v173, v[108:109] offset:4096
	v_max_f32_e32 v112, 0, v112
	v_max_f32_e32 v113, 0, v113
	v_max_f32_e32 v114, 0, v114
	v_max_f32_e32 v115, 0, v115
	v_mul_f32_e32 v112, v112, v112
	v_mul_f32_e32 v113, v113, v113
	v_mul_f32_e32 v114, v114, v114
	v_mul_f32_e32 v115, v115, v115
	v_cvt_pk_bf16_f32 v112, v112, v113
	v_cvt_pk_bf16_f32 v113, v114, v115
	ds_write_b64 v170, v[112:113] offset:6144
	v_max_f32_e32 v116, 0, v116
	v_max_f32_e32 v117, 0, v117
	v_max_f32_e32 v118, 0, v118
	v_max_f32_e32 v119, 0, v119
	v_mul_f32_e32 v116, v116, v116
	v_mul_f32_e32 v117, v117, v117
	v_mul_f32_e32 v118, v118, v118
	v_mul_f32_e32 v119, v119, v119
	v_cvt_pk_bf16_f32 v116, v116, v117
	v_cvt_pk_bf16_f32 v117, v118, v119
	ds_write_b64 v171, v[116:117] offset:6144
	v_max_f32_e32 v120, 0, v120
	v_max_f32_e32 v121, 0, v121
	v_max_f32_e32 v122, 0, v122
	v_max_f32_e32 v123, 0, v123
	v_mul_f32_e32 v120, v120, v120
	v_mul_f32_e32 v121, v121, v121
	v_mul_f32_e32 v122, v122, v122
	v_mul_f32_e32 v123, v123, v123
	v_cvt_pk_bf16_f32 v120, v120, v121
	v_cvt_pk_bf16_f32 v121, v122, v123
	ds_write_b64 v172, v[120:121] offset:6144
	v_max_f32_e32 v124, 0, v124
	v_max_f32_e32 v125, 0, v125
	v_max_f32_e32 v126, 0, v126
	v_max_f32_e32 v127, 0, v127
	v_mul_f32_e32 v124, v124, v124
	v_mul_f32_e32 v125, v125, v125
	v_mul_f32_e32 v126, v126, v126
	v_mul_f32_e32 v127, v127, v127
	v_cvt_pk_bf16_f32 v124, v124, v125
	v_cvt_pk_bf16_f32 v125, v126, v127
	ds_write_b64 v173, v[124:125] offset:6144
	s_waitcnt lgkmcnt(0)
; DEV u16 f2bf(float f) { return (u16)(pack2(f, f) & 0xffffu); }
; template <class F>
; DEV void acc_foreach(Acc& acc, int m0, int n0, F f) {
;   asm volatile("s_nop 7\n\ts_nop 7\n\ts_nop 3" ::: "memory");
;   const int tid = tidx_full();
;   const int wave = tid >> 6, lane = tid & 63;
;   const int wm = (wave >> 2) * 128, wn = (wave & 3) * 64;
;   const int lr = lane & 31, lh = lane >> 5;
; #pragma unroll
;   for (int i = 0; i < 4; ++i)
; #pragma unroll
;     for (int j = 0; j < 2; ++j)
; #pragma unroll
;       for (int r = 0; r < 16; ++r) {
;         const int m = m0 + wm + 32 * i + (r & 3) + 8 * (r >> 2) + 4 * lh;
;         const int n = n0 + wn + 32 * j + lr;
;         float v = acc[i][j][r];
;         f(m, n, v);
;         acc[i][j][r] = v;
;       }
; DEV void phase_ff1(const Params& p, int g, char* smem) {
;     ...
;     acc_foreach(acc, m0, n0, [&](int m, int n, float& v) {
;       const float r = fmaxf(v, 0.f);
;       AB[(size_t)m * 4096 + n] = f2bf(r * r);
;     });
	ds_read_b128 v[64:67], v168
	ds_read_b128 v[68:71], v168 offset:1024
	ds_read_b128 v[72:75], v168 offset:2048
	ds_read_b128 v[76:79], v168 offset:3072
	ds_read_b128 v[80:83], v168 offset:4096
	ds_read_b128 v[84:87], v168 offset:5120
	ds_read_b128 v[88:91], v168 offset:6144
	ds_read_b128 v[92:95], v168 offset:7168
	s_waitcnt lgkmcnt(7)
	global_store_dwordx4 v169, v[64:67], s[74:75]
	v_add_u32_e32 v169, 0x10000, v169
	s_waitcnt lgkmcnt(6)
	global_store_dwordx4 v169, v[68:71], s[74:75]
	v_add_u32_e32 v169, 0x10000, v169
	s_waitcnt lgkmcnt(5)
	global_store_dwordx4 v169, v[72:75], s[74:75]
	v_add_u32_e32 v169, 0x10000, v169
	s_waitcnt lgkmcnt(4)
	global_store_dwordx4 v169, v[76:79], s[74:75]
	v_add_u32_e32 v169, 0x10000, v169
	s_waitcnt lgkmcnt(3)
	global_store_dwordx4 v169, v[80:83], s[74:75]
	v_add_u32_e32 v169, 0x10000, v169
	s_waitcnt lgkmcnt(2)
	global_store_dwordx4 v169, v[84:87], s[74:75]
	v_add_u32_e32 v169, 0x10000, v169
	s_waitcnt lgkmcnt(1)
	global_store_dwordx4 v169, v[88:91], s[74:75]
	v_add_u32_e32 v169, 0x10000, v169
	s_waitcnt lgkmcnt(0)
	global_store_dwordx4 v169, v[92:95], s[74:75]
	v_add_u32_e32 v169, 0x10000, v169
	s_mov_b64 s[4:5], 0
	s_branch .LBB0_1110
